# removed all per-phase s_setprio flips from the six GEMM K-loops (on top of saddr-form LDS-DMA loads): arbitration by age only
# speedup vs baseline: 1.0125x; 1.0018x over previous
.LBB0_146:
	s_add_u32 s40, s34, 0xfff80080
	s_addc_u32 s41, s35, -1
	s_add_i32 s61, 0, 0x10000
	s_cmp_eq_u32 s60, 28
	s_cselect_b32 s43, s13, s41
	s_cselect_b32 s42, s56, s40
	s_cselect_b32 s41, s9, s59
	s_cselect_b32 s40, s57, s58
	s_add_i32 s64, 0, 0x14000
	v_add_u32_e32 v160, s61, v143
	v_add_u32_e32 v176, s64, v143
	ds_read_b128 v[148:151], v160
	ds_read_b128 v[152:155], v160 offset:1024
	ds_read_b128 v[156:159], v160 offset:2048
	ds_read_b128 v[160:163], v160 offset:3072
	ds_read_b128 v[164:167], v176
	ds_read_b128 v[168:171], v176 offset:1024
	ds_read_b128 v[172:175], v176 offset:2048
	ds_read_b128 v[176:179], v176 offset:3072
	s_add_i32 m0, s47, 0xc000
	ds_read_b128 v[180:183], v147
	ds_read_b128 v[184:187], v147 offset:1024
	ds_read_b128 v[188:191], v147 offset:2048
	ds_read_b128 v[192:195], v147 offset:3072
	ds_read_b128 v[202:205], v147 offset:4096
	ds_read_b128 v[214:217], v147 offset:5120
	ds_read_b128 v[218:221], v147 offset:6144
	ds_read_b128 v[222:225], v147 offset:7168
	global_load_lds_dwordx4 v138, s[34:35]
	s_add_i32 m0, s47, 0xe000
	s_nop 0
	global_load_lds_dwordx4 v140, s[34:35]
	s_waitcnt vmcnt(8)
	s_waitcnt lgkmcnt(0)
	s_barrier
	s_waitcnt lgkmcnt(0)
	v_mfma_f32_16x16x32_bf16 v[128:131], v[148:151], v[180:183], v[128:131]
	v_mfma_f32_16x16x32_bf16 v[120:123], v[156:159], v[180:183], v[120:123]
	v_mfma_f32_16x16x32_bf16 v[112:115], v[148:151], v[188:191], v[112:115]
	v_mfma_f32_16x16x32_bf16 v[104:107], v[156:159], v[188:191], v[104:107]
	v_mfma_f32_16x16x32_bf16 v[96:99], v[148:151], v[202:205], v[96:99]
	v_mfma_f32_16x16x32_bf16 v[88:91], v[156:159], v[202:205], v[88:91]
	v_mfma_f32_16x16x32_bf16 v[80:83], v[148:151], v[218:221], v[80:83]
	v_mfma_f32_16x16x32_bf16 v[72:75], v[156:159], v[218:221], v[72:75]
	v_mfma_f32_16x16x32_bf16 v[128:131], v[152:155], v[184:187], v[128:131]
	v_mfma_f32_16x16x32_bf16 v[120:123], v[160:163], v[184:187], v[120:123]
	v_mfma_f32_16x16x32_bf16 v[112:115], v[152:155], v[192:195], v[112:115]
	v_mfma_f32_16x16x32_bf16 v[104:107], v[160:163], v[192:195], v[104:107]
	v_mfma_f32_16x16x32_bf16 v[96:99], v[152:155], v[214:217], v[96:99]
	v_mfma_f32_16x16x32_bf16 v[88:91], v[160:163], v[214:217], v[88:91]
	v_mfma_f32_16x16x32_bf16 v[80:83], v[152:155], v[222:225], v[80:83]
	v_mfma_f32_16x16x32_bf16 v[72:75], v[160:163], v[222:225], v[72:75]
	v_mfma_f32_16x16x32_bf16 v[124:127], v[164:167], v[180:183], v[124:127]
	v_mfma_f32_16x16x32_bf16 v[116:119], v[172:175], v[180:183], v[116:119]
	v_mfma_f32_16x16x32_bf16 v[108:111], v[164:167], v[188:191], v[108:111]
	v_mfma_f32_16x16x32_bf16 v[100:103], v[172:175], v[188:191], v[100:103]
	v_mfma_f32_16x16x32_bf16 v[92:95], v[164:167], v[202:205], v[92:95]
	v_mfma_f32_16x16x32_bf16 v[84:87], v[172:175], v[202:205], v[84:87]
	v_mfma_f32_16x16x32_bf16 v[76:79], v[164:167], v[218:221], v[76:79]
	v_mfma_f32_16x16x32_bf16 v[68:71], v[172:175], v[218:221], v[68:71]
	v_mfma_f32_16x16x32_bf16 v[124:127], v[168:171], v[184:187], v[124:127]
	v_mfma_f32_16x16x32_bf16 v[116:119], v[176:179], v[184:187], v[116:119]
	v_mfma_f32_16x16x32_bf16 v[108:111], v[168:171], v[192:195], v[108:111]
	v_mfma_f32_16x16x32_bf16 v[100:103], v[176:179], v[192:195], v[100:103]
	v_mfma_f32_16x16x32_bf16 v[92:95], v[168:171], v[214:217], v[92:95]
	v_mfma_f32_16x16x32_bf16 v[84:87], v[176:179], v[214:217], v[84:87]
	v_mfma_f32_16x16x32_bf16 v[76:79], v[168:171], v[222:225], v[76:79]
	v_mfma_f32_16x16x32_bf16 v[68:71], v[176:179], v[222:225], v[68:71]
	s_barrier
	s_add_i32 s61, s61, s46
	s_mov_b32 m0, s61
	ds_read_b128 v[180:183], v147 offset:16384
	ds_read_b128 v[184:187], v147 offset:17408
	ds_read_b128 v[188:191], v147 offset:18432
	ds_read_b128 v[192:195], v147 offset:19456
	ds_read_b128 v[202:205], v147 offset:20480
	ds_read_b128 v[214:217], v147 offset:21504
	ds_read_b128 v[218:221], v147 offset:22528
	ds_read_b128 v[222:225], v147 offset:23552
	global_load_lds_dwordx4 v2, s[40:41]
	s_add_i32 m0, s61, 0x2000
	s_add_u32 s62, s40, 0x4000
	s_addc_u32 s63, s41, 0
	s_add_i32 s61, s64, s46
	global_load_lds_dwordx4 v132, s[40:41]
	s_mov_b32 m0, s61
	v_lshl_add_u64 v[228:229], s[42:43], 0, v[134:135]
	global_load_lds_dwordx4 v2, s[62:63]
	s_add_i32 m0, s61, 0x2000
	s_nop 0
	global_load_lds_dwordx4 v132, s[62:63]
	v_lshl_add_u64 v[226:227], s[42:43], 0, v[136:137]
	s_mov_b32 m0, s47
	s_nop 0
	global_load_lds_dwordx4 v136, s[42:43]
	s_mov_b32 m0, s48
	s_nop 0
	global_load_lds_dwordx4 v134, s[42:43]
	s_waitcnt vmcnt(8)
	s_waitcnt lgkmcnt(0)
	s_barrier
	s_waitcnt lgkmcnt(0)
	v_mfma_f32_16x16x32_bf16 v[64:67], v[148:151], v[180:183], v[64:67]
	v_mfma_f32_16x16x32_bf16 v[56:59], v[156:159], v[180:183], v[56:59]
	v_mfma_f32_16x16x32_bf16 v[48:51], v[148:151], v[188:191], v[48:51]
	v_mfma_f32_16x16x32_bf16 v[40:43], v[156:159], v[188:191], v[40:43]
	v_mfma_f32_16x16x32_bf16 v[32:35], v[148:151], v[202:205], v[32:35]
	v_mfma_f32_16x16x32_bf16 v[24:27], v[156:159], v[202:205], v[24:27]
	v_mfma_f32_16x16x32_bf16 v[16:19], v[148:151], v[218:221], v[16:19]
	v_mfma_f32_16x16x32_bf16 v[8:11], v[156:159], v[218:221], v[8:11]
	v_mfma_f32_16x16x32_bf16 v[64:67], v[152:155], v[184:187], v[64:67]
	v_mfma_f32_16x16x32_bf16 v[56:59], v[160:163], v[184:187], v[56:59]
	v_mfma_f32_16x16x32_bf16 v[48:51], v[152:155], v[192:195], v[48:51]
	v_mfma_f32_16x16x32_bf16 v[40:43], v[160:163], v[192:195], v[40:43]
	v_mfma_f32_16x16x32_bf16 v[32:35], v[152:155], v[214:217], v[32:35]
	v_mfma_f32_16x16x32_bf16 v[24:27], v[160:163], v[214:217], v[24:27]
	v_mfma_f32_16x16x32_bf16 v[16:19], v[152:155], v[222:225], v[16:19]
	v_mfma_f32_16x16x32_bf16 v[8:11], v[160:163], v[222:225], v[8:11]
	v_mfma_f32_16x16x32_bf16 v[60:63], v[164:167], v[180:183], v[60:63]
	v_mfma_f32_16x16x32_bf16 v[52:55], v[172:175], v[180:183], v[52:55]
	v_mfma_f32_16x16x32_bf16 v[44:47], v[164:167], v[188:191], v[44:47]
	v_mfma_f32_16x16x32_bf16 v[36:39], v[172:175], v[188:191], v[36:39]
	v_mfma_f32_16x16x32_bf16 v[28:31], v[164:167], v[202:205], v[28:31]
	v_mfma_f32_16x16x32_bf16 v[20:23], v[172:175], v[202:205], v[20:23]
	v_mfma_f32_16x16x32_bf16 v[12:15], v[164:167], v[218:221], v[12:15]
	v_mfma_f32_16x16x32_bf16 v[4:7], v[172:175], v[218:221], v[4:7]
	v_mfma_f32_16x16x32_bf16 v[60:63], v[168:171], v[184:187], v[60:63]
	v_mfma_f32_16x16x32_bf16 v[52:55], v[176:179], v[184:187], v[52:55]
	v_mfma_f32_16x16x32_bf16 v[44:47], v[168:171], v[192:195], v[44:47]
	v_mfma_f32_16x16x32_bf16 v[36:39], v[176:179], v[192:195], v[36:39]
	v_mfma_f32_16x16x32_bf16 v[28:31], v[168:171], v[214:217], v[28:31]
	v_mfma_f32_16x16x32_bf16 v[20:23], v[176:179], v[214:217], v[20:23]
	v_mfma_f32_16x16x32_bf16 v[12:15], v[168:171], v[222:225], v[12:15]
	v_mfma_f32_16x16x32_bf16 v[4:7], v[176:179], v[222:225], v[4:7]
	s_barrier
	s_add_i32 s61, 0, 0x18000
	s_add_i32 s62, 0, 0x1c000
	v_add_u32_e32 v160, s61, v143
	v_add_u32_e32 v176, s62, v143
	ds_read_b128 v[148:151], v160
	ds_read_b128 v[152:155], v160 offset:1024
	ds_read_b128 v[156:159], v160 offset:2048
	ds_read_b128 v[160:163], v160 offset:3072
	ds_read_b128 v[164:167], v176
	ds_read_b128 v[168:171], v176 offset:1024
	ds_read_b128 v[172:175], v176 offset:2048
	ds_read_b128 v[176:179], v176 offset:3072
	s_add_u32 s42, s42, 0x80000
	s_addc_u32 s43, s43, 0
	s_mov_b32 m0, s49
	ds_read_b128 v[180:183], v147 offset:32768
	ds_read_b128 v[184:187], v147 offset:33792
	ds_read_b128 v[188:191], v147 offset:34816
	ds_read_b128 v[192:195], v147 offset:35840
	ds_read_b128 v[202:205], v147 offset:36864
	ds_read_b128 v[214:217], v147 offset:37888
	ds_read_b128 v[218:221], v147 offset:38912
	ds_read_b128 v[222:225], v147 offset:39936
	global_load_lds_dwordx4 v136, s[42:43]
	s_mov_b32 m0, s50
	s_nop 0
	global_load_lds_dwordx4 v134, s[42:43]
	s_waitcnt vmcnt(8)
	s_waitcnt lgkmcnt(0)
	s_barrier
	s_waitcnt lgkmcnt(0)
	v_mfma_f32_16x16x32_bf16 v[128:131], v[148:151], v[180:183], v[128:131]
	v_mfma_f32_16x16x32_bf16 v[120:123], v[156:159], v[180:183], v[120:123]
	v_mfma_f32_16x16x32_bf16 v[112:115], v[148:151], v[188:191], v[112:115]
	v_mfma_f32_16x16x32_bf16 v[104:107], v[156:159], v[188:191], v[104:107]
	v_mfma_f32_16x16x32_bf16 v[96:99], v[148:151], v[202:205], v[96:99]
	v_mfma_f32_16x16x32_bf16 v[88:91], v[156:159], v[202:205], v[88:91]
	v_mfma_f32_16x16x32_bf16 v[80:83], v[148:151], v[218:221], v[80:83]
	v_mfma_f32_16x16x32_bf16 v[72:75], v[156:159], v[218:221], v[72:75]
	v_mfma_f32_16x16x32_bf16 v[128:131], v[152:155], v[184:187], v[128:131]
	v_mfma_f32_16x16x32_bf16 v[120:123], v[160:163], v[184:187], v[120:123]
	v_mfma_f32_16x16x32_bf16 v[112:115], v[152:155], v[192:195], v[112:115]
	v_mfma_f32_16x16x32_bf16 v[104:107], v[160:163], v[192:195], v[104:107]
	v_mfma_f32_16x16x32_bf16 v[96:99], v[152:155], v[214:217], v[96:99]
	v_mfma_f32_16x16x32_bf16 v[88:91], v[160:163], v[214:217], v[88:91]
	v_mfma_f32_16x16x32_bf16 v[80:83], v[152:155], v[222:225], v[80:83]
	v_mfma_f32_16x16x32_bf16 v[72:75], v[160:163], v[222:225], v[72:75]
	v_mfma_f32_16x16x32_bf16 v[124:127], v[164:167], v[180:183], v[124:127]
	v_mfma_f32_16x16x32_bf16 v[116:119], v[172:175], v[180:183], v[116:119]
	v_mfma_f32_16x16x32_bf16 v[108:111], v[164:167], v[188:191], v[108:111]
	v_mfma_f32_16x16x32_bf16 v[100:103], v[172:175], v[188:191], v[100:103]
	v_mfma_f32_16x16x32_bf16 v[92:95], v[164:167], v[202:205], v[92:95]
	v_mfma_f32_16x16x32_bf16 v[84:87], v[172:175], v[202:205], v[84:87]
	v_mfma_f32_16x16x32_bf16 v[76:79], v[164:167], v[218:221], v[76:79]
	v_mfma_f32_16x16x32_bf16 v[68:71], v[172:175], v[218:221], v[68:71]
	v_mfma_f32_16x16x32_bf16 v[124:127], v[168:171], v[184:187], v[124:127]
	v_mfma_f32_16x16x32_bf16 v[116:119], v[176:179], v[184:187], v[116:119]
	v_mfma_f32_16x16x32_bf16 v[108:111], v[168:171], v[192:195], v[108:111]
	v_mfma_f32_16x16x32_bf16 v[100:103], v[176:179], v[192:195], v[100:103]
	v_mfma_f32_16x16x32_bf16 v[92:95], v[168:171], v[214:217], v[92:95]
	v_mfma_f32_16x16x32_bf16 v[84:87], v[176:179], v[214:217], v[84:87]
	v_mfma_f32_16x16x32_bf16 v[76:79], v[168:171], v[222:225], v[76:79]
	v_mfma_f32_16x16x32_bf16 v[68:71], v[176:179], v[222:225], v[68:71]
	s_barrier
	s_add_u32 s42, s40, 0x8000
	s_addc_u32 s43, s41, 0
	s_add_i32 s61, s61, s46
	s_mov_b32 m0, s61
	ds_read_b128 v[180:183], v147 offset:49152
	ds_read_b128 v[184:187], v147 offset:50176
	ds_read_b128 v[188:191], v147 offset:51200
	ds_read_b128 v[192:195], v147 offset:52224
	ds_read_b128 v[202:205], v147 offset:53248
	ds_read_b128 v[214:217], v147 offset:54272
	ds_read_b128 v[218:221], v147 offset:55296
	ds_read_b128 v[222:225], v147 offset:56320
	global_load_lds_dwordx4 v2, s[42:43]
	s_add_i32 m0, s61, 0x2000
	s_add_u32 s40, s40, 0xc000
	v_lshl_add_u64 v[230:231], s[42:43], 0, v[132:133]
	s_addc_u32 s41, s41, 0
	s_add_i32 s42, s62, s46
	global_load_lds_dwordx4 v[230:231], off
	s_mov_b32 m0, s42
	v_lshl_add_u64 v[226:227], v[226:227], 0, s[4:5]
	global_load_lds_dwordx4 v2, s[40:41]
	s_add_i32 m0, s42, 0x2000
	s_nop 0
	global_load_lds_dwordx4 v132, s[40:41]
	s_mov_b32 m0, s51
	s_nop 0
	global_load_lds_dwordx4 v[226:227], off
	v_lshl_add_u64 v[226:227], v[228:229], 0, s[4:5]
	s_mov_b32 m0, s52
	s_nop 0
	global_load_lds_dwordx4 v[226:227], off
	s_waitcnt vmcnt(8)
	s_waitcnt lgkmcnt(0)
	s_barrier
	s_waitcnt lgkmcnt(0)
	v_mfma_f32_16x16x32_bf16 v[64:67], v[148:151], v[180:183], v[64:67]
	v_mfma_f32_16x16x32_bf16 v[56:59], v[156:159], v[180:183], v[56:59]
	v_mfma_f32_16x16x32_bf16 v[48:51], v[148:151], v[188:191], v[48:51]
	v_mfma_f32_16x16x32_bf16 v[40:43], v[156:159], v[188:191], v[40:43]
	v_mfma_f32_16x16x32_bf16 v[32:35], v[148:151], v[202:205], v[32:35]
	v_mfma_f32_16x16x32_bf16 v[24:27], v[156:159], v[202:205], v[24:27]
	v_mfma_f32_16x16x32_bf16 v[16:19], v[148:151], v[218:221], v[16:19]
	v_mfma_f32_16x16x32_bf16 v[8:11], v[156:159], v[218:221], v[8:11]
	v_mfma_f32_16x16x32_bf16 v[64:67], v[152:155], v[184:187], v[64:67]
	v_mfma_f32_16x16x32_bf16 v[56:59], v[160:163], v[184:187], v[56:59]
	v_mfma_f32_16x16x32_bf16 v[48:51], v[152:155], v[192:195], v[48:51]
	v_mfma_f32_16x16x32_bf16 v[40:43], v[160:163], v[192:195], v[40:43]
	v_mfma_f32_16x16x32_bf16 v[32:35], v[152:155], v[214:217], v[32:35]
	v_mfma_f32_16x16x32_bf16 v[24:27], v[160:163], v[214:217], v[24:27]
	v_mfma_f32_16x16x32_bf16 v[16:19], v[152:155], v[222:225], v[16:19]
	v_mfma_f32_16x16x32_bf16 v[8:11], v[160:163], v[222:225], v[8:11]
	v_mfma_f32_16x16x32_bf16 v[60:63], v[164:167], v[180:183], v[60:63]
	v_mfma_f32_16x16x32_bf16 v[52:55], v[172:175], v[180:183], v[52:55]
	v_mfma_f32_16x16x32_bf16 v[44:47], v[164:167], v[188:191], v[44:47]
	v_mfma_f32_16x16x32_bf16 v[36:39], v[172:175], v[188:191], v[36:39]
	v_mfma_f32_16x16x32_bf16 v[28:31], v[164:167], v[202:205], v[28:31]
	v_mfma_f32_16x16x32_bf16 v[20:23], v[172:175], v[202:205], v[20:23]
	v_mfma_f32_16x16x32_bf16 v[12:15], v[164:167], v[218:221], v[12:15]
	v_mfma_f32_16x16x32_bf16 v[4:7], v[172:175], v[218:221], v[4:7]
	v_mfma_f32_16x16x32_bf16 v[60:63], v[168:171], v[184:187], v[60:63]
	v_mfma_f32_16x16x32_bf16 v[52:55], v[176:179], v[184:187], v[52:55]
	v_mfma_f32_16x16x32_bf16 v[44:47], v[168:171], v[192:195], v[44:47]
	v_mfma_f32_16x16x32_bf16 v[36:39], v[176:179], v[192:195], v[36:39]
	v_mfma_f32_16x16x32_bf16 v[28:31], v[168:171], v[214:217], v[28:31]
	v_mfma_f32_16x16x32_bf16 v[20:23], v[176:179], v[214:217], v[20:23]
	v_mfma_f32_16x16x32_bf16 v[12:15], v[168:171], v[222:225], v[12:15]
	v_mfma_f32_16x16x32_bf16 v[4:7], v[176:179], v[222:225], v[4:7]
	s_barrier
	s_add_i32 s60, s60, 2
	s_add_u32 s58, s58, 0x10000
	s_addc_u32 s59, s59, 0
	s_add_u32 s34, s34, 0x100
	s_addc_u32 s35, s35, 0
	s_cmp_gt_u32 s60, 29
	s_cbranch_scc0 .LBB0_146
	s_and_b64 vcc, exec, s[6:7]
	s_cbranch_vccz .LBB0_149
	s_barrier

.LBB0_223:
	s_add_u32 s22, s14, 0x100
	s_addc_u32 s23, s15, 0
	s_add_i32 s67, 0, 0x10000
	s_cmpk_eq_i32 s66, 0x54
	s_cselect_b32 s49, s9, s23
	s_cselect_b32 s48, s8, s22
	s_cselect_b32 s35, s13, s65
	s_cselect_b32 s34, s12, s64
	s_add_i32 s68, 0, 0x14000
	v_add_u32_e32 v136, s67, v202
	v_add_u32_e32 v156, s68, v202
	ds_read_b128 v[108:111], v136
	ds_read_b128 v[116:119], v136 offset:1024
	ds_read_b128 v[128:131], v136 offset:2048
	ds_read_b128 v[136:139], v136 offset:3072
	ds_read_b128 v[140:143], v156
	ds_read_b128 v[144:147], v156 offset:1024
	ds_read_b128 v[148:151], v156 offset:2048
	ds_read_b128 v[156:159], v156 offset:3072
	s_add_i32 m0, s53, 0xc000
	ds_read_b128 v[164:167], v204
	ds_read_b128 v[168:171], v204 offset:1024
	ds_read_b128 v[172:175], v204 offset:2048
	ds_read_b128 v[176:179], v204 offset:3072
	ds_read_b128 v[180:183], v204 offset:4096
	ds_read_b128 v[184:187], v204 offset:5120
	ds_read_b128 v[188:191], v204 offset:6144
	ds_read_b128 v[192:195], v204 offset:7168
	global_load_lds_dwordx4 v220, s[14:15]
	s_add_i32 m0, s53, 0xe000
	s_nop 0
	global_load_lds_dwordx4 v222, s[14:15]
	s_waitcnt vmcnt(8)
	s_waitcnt lgkmcnt(0)
	s_barrier
	s_waitcnt lgkmcnt(0)
	v_mfma_f32_16x16x32_bf16 v[160:163], v[108:111], v[164:167], v[160:163]
	v_mfma_f32_16x16x32_bf16 v[152:155], v[128:131], v[164:167], v[152:155]
	v_mfma_f32_16x16x32_bf16 v[120:123], v[108:111], v[172:175], v[120:123]
	v_mfma_f32_16x16x32_bf16 v[112:115], v[128:131], v[172:175], v[112:115]
	v_mfma_f32_16x16x32_bf16 v[96:99], v[108:111], v[180:183], v[96:99]
	v_mfma_f32_16x16x32_bf16 v[92:95], v[128:131], v[180:183], v[92:95]
	v_mfma_f32_16x16x32_bf16 v[80:83], v[108:111], v[188:191], v[80:83]
	v_mfma_f32_16x16x32_bf16 v[76:79], v[128:131], v[188:191], v[76:79]
	v_mfma_f32_16x16x32_bf16 v[160:163], v[116:119], v[168:171], v[160:163]
	v_mfma_f32_16x16x32_bf16 v[152:155], v[136:139], v[168:171], v[152:155]
	v_mfma_f32_16x16x32_bf16 v[120:123], v[116:119], v[176:179], v[120:123]
	v_mfma_f32_16x16x32_bf16 v[112:115], v[136:139], v[176:179], v[112:115]
	v_mfma_f32_16x16x32_bf16 v[96:99], v[116:119], v[184:187], v[96:99]
	v_mfma_f32_16x16x32_bf16 v[92:95], v[136:139], v[184:187], v[92:95]
	v_mfma_f32_16x16x32_bf16 v[80:83], v[116:119], v[192:195], v[80:83]
	v_mfma_f32_16x16x32_bf16 v[76:79], v[136:139], v[192:195], v[76:79]
	v_mfma_f32_16x16x32_bf16 v[132:135], v[140:143], v[164:167], v[132:135]
	v_mfma_f32_16x16x32_bf16 v[124:127], v[148:151], v[164:167], v[124:127]
	v_mfma_f32_16x16x32_bf16 v[104:107], v[140:143], v[172:175], v[104:107]
	v_mfma_f32_16x16x32_bf16 v[100:103], v[148:151], v[172:175], v[100:103]
	v_mfma_f32_16x16x32_bf16 v[88:91], v[140:143], v[180:183], v[88:91]
	v_mfma_f32_16x16x32_bf16 v[84:87], v[148:151], v[180:183], v[84:87]
	v_mfma_f32_16x16x32_bf16 v[72:75], v[140:143], v[188:191], v[72:75]
	v_mfma_f32_16x16x32_bf16 v[68:71], v[148:151], v[188:191], v[68:71]
	v_mfma_f32_16x16x32_bf16 v[132:135], v[144:147], v[168:171], v[132:135]
	v_mfma_f32_16x16x32_bf16 v[124:127], v[156:159], v[168:171], v[124:127]
	v_mfma_f32_16x16x32_bf16 v[104:107], v[144:147], v[176:179], v[104:107]
	v_mfma_f32_16x16x32_bf16 v[100:103], v[156:159], v[176:179], v[100:103]
	v_mfma_f32_16x16x32_bf16 v[88:91], v[144:147], v[184:187], v[88:91]
	v_mfma_f32_16x16x32_bf16 v[84:87], v[156:159], v[184:187], v[84:87]
	v_mfma_f32_16x16x32_bf16 v[72:75], v[144:147], v[192:195], v[72:75]
	v_mfma_f32_16x16x32_bf16 v[68:71], v[156:159], v[192:195], v[68:71]
	s_barrier
	s_add_i32 s14, s67, s52
	s_mov_b32 m0, s14
	ds_read_b128 v[164:167], v204 offset:16384
	ds_read_b128 v[168:171], v204 offset:17408
	ds_read_b128 v[172:175], v204 offset:18432
	ds_read_b128 v[176:179], v204 offset:19456
	ds_read_b128 v[180:183], v204 offset:20480
	ds_read_b128 v[184:187], v204 offset:21504
	ds_read_b128 v[188:191], v204 offset:22528
	ds_read_b128 v[192:195], v204 offset:23552
	global_load_lds_dwordx4 v2, s[34:35]
	s_add_i32 m0, s14, 0x2000
	s_add_u32 s14, s34, 0x4000
	s_addc_u32 s15, s35, 0
	s_add_i32 s67, s68, s52
	global_load_lds_dwordx4 v214, s[34:35]
	s_mov_b32 m0, s67
	v_lshl_add_u64 v[226:227], s[48:49], 0, v[216:217]
	global_load_lds_dwordx4 v2, s[14:15]
	s_add_i32 m0, s67, 0x2000
	s_nop 0
	global_load_lds_dwordx4 v214, s[14:15]
	v_lshl_add_u64 v[224:225], s[48:49], 0, v[218:219]
	s_mov_b32 m0, s53
	s_nop 0
	global_load_lds_dwordx4 v218, s[48:49]
	s_mov_b32 m0, s54
	s_nop 0
	global_load_lds_dwordx4 v216, s[48:49]
	s_waitcnt vmcnt(8)
	s_waitcnt lgkmcnt(0)
	s_barrier
	s_waitcnt lgkmcnt(0)
	v_mfma_f32_16x16x32_bf16 v[64:67], v[108:111], v[164:167], v[64:67]
	v_mfma_f32_16x16x32_bf16 v[60:63], v[128:131], v[164:167], v[60:63]
	v_mfma_f32_16x16x32_bf16 v[48:51], v[108:111], v[172:175], v[48:51]
	v_mfma_f32_16x16x32_bf16 v[44:47], v[128:131], v[172:175], v[44:47]
	v_mfma_f32_16x16x32_bf16 v[32:35], v[108:111], v[180:183], v[32:35]
	v_mfma_f32_16x16x32_bf16 v[28:31], v[128:131], v[180:183], v[28:31]
	v_mfma_f32_16x16x32_bf16 v[16:19], v[108:111], v[188:191], v[16:19]
	v_mfma_f32_16x16x32_bf16 v[12:15], v[128:131], v[188:191], v[12:15]
	v_mfma_f32_16x16x32_bf16 v[64:67], v[116:119], v[168:171], v[64:67]
	v_mfma_f32_16x16x32_bf16 v[60:63], v[136:139], v[168:171], v[60:63]
	v_mfma_f32_16x16x32_bf16 v[48:51], v[116:119], v[176:179], v[48:51]
	v_mfma_f32_16x16x32_bf16 v[44:47], v[136:139], v[176:179], v[44:47]
	v_mfma_f32_16x16x32_bf16 v[32:35], v[116:119], v[184:187], v[32:35]
	v_mfma_f32_16x16x32_bf16 v[28:31], v[136:139], v[184:187], v[28:31]
	v_mfma_f32_16x16x32_bf16 v[16:19], v[116:119], v[192:195], v[16:19]
	v_mfma_f32_16x16x32_bf16 v[12:15], v[136:139], v[192:195], v[12:15]
	v_mfma_f32_16x16x32_bf16 v[56:59], v[140:143], v[164:167], v[56:59]
	v_mfma_f32_16x16x32_bf16 v[52:55], v[148:151], v[164:167], v[52:55]
	v_mfma_f32_16x16x32_bf16 v[40:43], v[140:143], v[172:175], v[40:43]
	v_mfma_f32_16x16x32_bf16 v[36:39], v[148:151], v[172:175], v[36:39]
	v_mfma_f32_16x16x32_bf16 v[24:27], v[140:143], v[180:183], v[24:27]
	v_mfma_f32_16x16x32_bf16 v[20:23], v[148:151], v[180:183], v[20:23]
	v_mfma_f32_16x16x32_bf16 v[8:11], v[140:143], v[188:191], v[8:11]
	v_mfma_f32_16x16x32_bf16 v[4:7], v[148:151], v[188:191], v[4:7]
	v_mfma_f32_16x16x32_bf16 v[56:59], v[144:147], v[168:171], v[56:59]
	v_mfma_f32_16x16x32_bf16 v[52:55], v[156:159], v[168:171], v[52:55]
	v_mfma_f32_16x16x32_bf16 v[40:43], v[144:147], v[176:179], v[40:43]
	v_mfma_f32_16x16x32_bf16 v[36:39], v[156:159], v[176:179], v[36:39]
	v_mfma_f32_16x16x32_bf16 v[24:27], v[144:147], v[184:187], v[24:27]
	v_mfma_f32_16x16x32_bf16 v[20:23], v[156:159], v[184:187], v[20:23]
	v_mfma_f32_16x16x32_bf16 v[8:11], v[144:147], v[192:195], v[8:11]
	v_mfma_f32_16x16x32_bf16 v[4:7], v[156:159], v[192:195], v[4:7]
	s_barrier
	s_add_i32 s67, 0, 0x18000
	s_add_i32 s68, 0, 0x1c000
	v_add_u32_e32 v136, s67, v202
	v_add_u32_e32 v156, s68, v202
	ds_read_b128 v[108:111], v136
	ds_read_b128 v[116:119], v136 offset:1024
	ds_read_b128 v[128:131], v136 offset:2048
	ds_read_b128 v[136:139], v136 offset:3072
	ds_read_b128 v[140:143], v156
	ds_read_b128 v[144:147], v156 offset:1024
	ds_read_b128 v[148:151], v156 offset:2048
	ds_read_b128 v[156:159], v156 offset:3072
	s_add_u32 s14, s48, 0x160000
	s_addc_u32 s15, s49, 0
	s_mov_b32 m0, s55
	ds_read_b128 v[164:167], v204 offset:32768
	ds_read_b128 v[168:171], v204 offset:33792
	ds_read_b128 v[172:175], v204 offset:34816
	ds_read_b128 v[176:179], v204 offset:35840
	ds_read_b128 v[180:183], v204 offset:36864
	ds_read_b128 v[184:187], v204 offset:37888
	ds_read_b128 v[188:191], v204 offset:38912
	ds_read_b128 v[192:195], v204 offset:39936
	global_load_lds_dwordx4 v218, s[14:15]
	s_mov_b32 m0, s56
	s_nop 0
	global_load_lds_dwordx4 v216, s[14:15]
	s_waitcnt vmcnt(8)
	s_waitcnt lgkmcnt(0)
	s_barrier
	s_waitcnt lgkmcnt(0)
	v_mfma_f32_16x16x32_bf16 v[160:163], v[108:111], v[164:167], v[160:163]
	v_mfma_f32_16x16x32_bf16 v[152:155], v[128:131], v[164:167], v[152:155]
	v_mfma_f32_16x16x32_bf16 v[120:123], v[108:111], v[172:175], v[120:123]
	v_mfma_f32_16x16x32_bf16 v[112:115], v[128:131], v[172:175], v[112:115]
	v_mfma_f32_16x16x32_bf16 v[96:99], v[108:111], v[180:183], v[96:99]
	v_mfma_f32_16x16x32_bf16 v[92:95], v[128:131], v[180:183], v[92:95]
	v_mfma_f32_16x16x32_bf16 v[80:83], v[108:111], v[188:191], v[80:83]
	v_mfma_f32_16x16x32_bf16 v[76:79], v[128:131], v[188:191], v[76:79]
	v_mfma_f32_16x16x32_bf16 v[160:163], v[116:119], v[168:171], v[160:163]
	v_mfma_f32_16x16x32_bf16 v[152:155], v[136:139], v[168:171], v[152:155]
	v_mfma_f32_16x16x32_bf16 v[120:123], v[116:119], v[176:179], v[120:123]
	v_mfma_f32_16x16x32_bf16 v[112:115], v[136:139], v[176:179], v[112:115]
	v_mfma_f32_16x16x32_bf16 v[96:99], v[116:119], v[184:187], v[96:99]
	v_mfma_f32_16x16x32_bf16 v[92:95], v[136:139], v[184:187], v[92:95]
	v_mfma_f32_16x16x32_bf16 v[80:83], v[116:119], v[192:195], v[80:83]
	v_mfma_f32_16x16x32_bf16 v[76:79], v[136:139], v[192:195], v[76:79]
	v_mfma_f32_16x16x32_bf16 v[132:135], v[140:143], v[164:167], v[132:135]
	v_mfma_f32_16x16x32_bf16 v[124:127], v[148:151], v[164:167], v[124:127]
	v_mfma_f32_16x16x32_bf16 v[104:107], v[140:143], v[172:175], v[104:107]
	v_mfma_f32_16x16x32_bf16 v[100:103], v[148:151], v[172:175], v[100:103]
	v_mfma_f32_16x16x32_bf16 v[88:91], v[140:143], v[180:183], v[88:91]
	v_mfma_f32_16x16x32_bf16 v[84:87], v[148:151], v[180:183], v[84:87]
	v_mfma_f32_16x16x32_bf16 v[72:75], v[140:143], v[188:191], v[72:75]
	v_mfma_f32_16x16x32_bf16 v[68:71], v[148:151], v[188:191], v[68:71]
	v_mfma_f32_16x16x32_bf16 v[132:135], v[144:147], v[168:171], v[132:135]
	v_mfma_f32_16x16x32_bf16 v[124:127], v[156:159], v[168:171], v[124:127]
	v_mfma_f32_16x16x32_bf16 v[104:107], v[144:147], v[176:179], v[104:107]
	v_mfma_f32_16x16x32_bf16 v[100:103], v[156:159], v[176:179], v[100:103]
	v_mfma_f32_16x16x32_bf16 v[88:91], v[144:147], v[184:187], v[88:91]
	v_mfma_f32_16x16x32_bf16 v[84:87], v[156:159], v[184:187], v[84:87]
	v_mfma_f32_16x16x32_bf16 v[72:75], v[144:147], v[192:195], v[72:75]
	v_mfma_f32_16x16x32_bf16 v[68:71], v[156:159], v[192:195], v[68:71]
	s_barrier
	s_add_u32 s14, s34, 0x8000
	s_addc_u32 s15, s35, 0
	s_add_i32 s48, s67, s52
	s_mov_b32 m0, s48
	ds_read_b128 v[164:167], v204 offset:49152
	ds_read_b128 v[168:171], v204 offset:50176
	ds_read_b128 v[172:175], v204 offset:51200
	ds_read_b128 v[176:179], v204 offset:52224
	ds_read_b128 v[180:183], v204 offset:53248
	ds_read_b128 v[184:187], v204 offset:54272
	ds_read_b128 v[188:191], v204 offset:55296
	ds_read_b128 v[192:195], v204 offset:56320
	global_load_lds_dwordx4 v2, s[14:15]
	s_add_i32 m0, s48, 0x2000
	v_lshl_add_u64 v[228:229], s[14:15], 0, v[214:215]
	s_add_u32 s14, s34, 0xc000
	s_addc_u32 s15, s35, 0
	s_add_i32 s34, s68, s52
	global_load_lds_dwordx4 v[228:229], off
	s_mov_b32 m0, s34
	v_lshl_add_u64 v[224:225], v[224:225], 0, s[4:5]
	global_load_lds_dwordx4 v2, s[14:15]
	s_add_i32 m0, s34, 0x2000
	s_nop 0
	global_load_lds_dwordx4 v214, s[14:15]
	s_mov_b32 m0, s57
	s_nop 0
	global_load_lds_dwordx4 v[224:225], off
	v_lshl_add_u64 v[224:225], v[226:227], 0, s[4:5]
	s_mov_b32 m0, s58
	s_nop 0
	global_load_lds_dwordx4 v[224:225], off
	s_waitcnt vmcnt(8)
	s_waitcnt lgkmcnt(0)
	s_barrier
	s_waitcnt lgkmcnt(0)
	v_mfma_f32_16x16x32_bf16 v[64:67], v[108:111], v[164:167], v[64:67]
	v_mfma_f32_16x16x32_bf16 v[60:63], v[128:131], v[164:167], v[60:63]
	v_mfma_f32_16x16x32_bf16 v[48:51], v[108:111], v[172:175], v[48:51]
	v_mfma_f32_16x16x32_bf16 v[44:47], v[128:131], v[172:175], v[44:47]
	v_mfma_f32_16x16x32_bf16 v[32:35], v[108:111], v[180:183], v[32:35]
	v_mfma_f32_16x16x32_bf16 v[28:31], v[128:131], v[180:183], v[28:31]
	v_mfma_f32_16x16x32_bf16 v[16:19], v[108:111], v[188:191], v[16:19]
	v_mfma_f32_16x16x32_bf16 v[12:15], v[128:131], v[188:191], v[12:15]
	v_mfma_f32_16x16x32_bf16 v[64:67], v[116:119], v[168:171], v[64:67]
	v_mfma_f32_16x16x32_bf16 v[60:63], v[136:139], v[168:171], v[60:63]
	v_mfma_f32_16x16x32_bf16 v[48:51], v[116:119], v[176:179], v[48:51]
	v_mfma_f32_16x16x32_bf16 v[44:47], v[136:139], v[176:179], v[44:47]
	v_mfma_f32_16x16x32_bf16 v[32:35], v[116:119], v[184:187], v[32:35]
	v_mfma_f32_16x16x32_bf16 v[28:31], v[136:139], v[184:187], v[28:31]
	v_mfma_f32_16x16x32_bf16 v[16:19], v[116:119], v[192:195], v[16:19]
	v_mfma_f32_16x16x32_bf16 v[12:15], v[136:139], v[192:195], v[12:15]
	v_mfma_f32_16x16x32_bf16 v[56:59], v[140:143], v[164:167], v[56:59]
	v_mfma_f32_16x16x32_bf16 v[52:55], v[148:151], v[164:167], v[52:55]
	v_mfma_f32_16x16x32_bf16 v[40:43], v[140:143], v[172:175], v[40:43]
	v_mfma_f32_16x16x32_bf16 v[36:39], v[148:151], v[172:175], v[36:39]
	v_mfma_f32_16x16x32_bf16 v[24:27], v[140:143], v[180:183], v[24:27]
	v_mfma_f32_16x16x32_bf16 v[20:23], v[148:151], v[180:183], v[20:23]
	v_mfma_f32_16x16x32_bf16 v[8:11], v[140:143], v[188:191], v[8:11]
	v_mfma_f32_16x16x32_bf16 v[4:7], v[148:151], v[188:191], v[4:7]
	v_mfma_f32_16x16x32_bf16 v[56:59], v[144:147], v[168:171], v[56:59]
	v_mfma_f32_16x16x32_bf16 v[52:55], v[156:159], v[168:171], v[52:55]
	v_mfma_f32_16x16x32_bf16 v[40:43], v[144:147], v[176:179], v[40:43]
	v_mfma_f32_16x16x32_bf16 v[36:39], v[156:159], v[176:179], v[36:39]
	v_mfma_f32_16x16x32_bf16 v[24:27], v[144:147], v[184:187], v[24:27]
	v_mfma_f32_16x16x32_bf16 v[20:23], v[156:159], v[184:187], v[20:23]
	v_mfma_f32_16x16x32_bf16 v[8:11], v[144:147], v[192:195], v[8:11]
	v_mfma_f32_16x16x32_bf16 v[4:7], v[156:159], v[192:195], v[4:7]
	s_barrier
	s_add_i32 s66, s66, 2
	s_add_u32 s64, s64, 0x10000
	s_addc_u32 s65, s65, 0
	s_cmpk_gt_u32 s66, 0x55
	s_mov_b64 s[14:15], s[22:23]
	s_cbranch_scc0 .LBB0_223
	s_and_b64 vcc, exec, s[6:7]
	s_cbranch_vccz .LBB0_226
	s_barrier

.LBB0_326:
	s_add_u32 s40, s34, 0xfff80080
	s_addc_u32 s41, s35, -1
	s_add_i32 s59, 0, 0x10000
	s_cmp_eq_u32 s58, 28
	s_cselect_b32 s43, s13, s41
	s_cselect_b32 s42, s54, s40
	s_cselect_b32 s41, s9, s57
	s_cselect_b32 s40, s55, s56
	s_add_i32 s62, 0, 0x14000
	v_add_u32_e32 v160, s59, v147
	v_add_u32_e32 v176, s62, v147
	ds_read_b128 v[142:145], v160
	ds_read_b128 v[152:155], v160 offset:1024
	ds_read_b128 v[156:159], v160 offset:2048
	ds_read_b128 v[160:163], v160 offset:3072
	ds_read_b128 v[164:167], v176
	ds_read_b128 v[168:171], v176 offset:1024
	ds_read_b128 v[172:175], v176 offset:2048
	ds_read_b128 v[176:179], v176 offset:3072
	s_add_i32 m0, s45, 0xc000
	ds_read_b128 v[180:183], v151
	ds_read_b128 v[184:187], v151 offset:1024
	ds_read_b128 v[188:191], v151 offset:2048
	ds_read_b128 v[192:195], v151 offset:3072
	ds_read_b128 v[202:205], v151 offset:4096
	ds_read_b128 v[214:217], v151 offset:5120
	ds_read_b128 v[218:221], v151 offset:6144
	ds_read_b128 v[222:225], v151 offset:7168
	global_load_lds_dwordx4 v138, s[34:35]
	s_add_i32 m0, s45, 0xe000
	s_nop 0
	global_load_lds_dwordx4 v140, s[34:35]
	s_waitcnt vmcnt(8)
	s_waitcnt lgkmcnt(0)
	s_barrier
	s_waitcnt lgkmcnt(0)
	v_mfma_f32_16x16x32_bf16 v[128:131], v[142:145], v[180:183], v[128:131]
	v_mfma_f32_16x16x32_bf16 v[124:127], v[156:159], v[180:183], v[124:127]
	v_mfma_f32_16x16x32_bf16 v[112:115], v[142:145], v[188:191], v[112:115]
	v_mfma_f32_16x16x32_bf16 v[108:111], v[156:159], v[188:191], v[108:111]
	v_mfma_f32_16x16x32_bf16 v[96:99], v[142:145], v[202:205], v[96:99]
	v_mfma_f32_16x16x32_bf16 v[92:95], v[156:159], v[202:205], v[92:95]
	v_mfma_f32_16x16x32_bf16 v[80:83], v[142:145], v[218:221], v[80:83]
	v_mfma_f32_16x16x32_bf16 v[76:79], v[156:159], v[218:221], v[76:79]
	v_mfma_f32_16x16x32_bf16 v[128:131], v[152:155], v[184:187], v[128:131]
	v_mfma_f32_16x16x32_bf16 v[124:127], v[160:163], v[184:187], v[124:127]
	v_mfma_f32_16x16x32_bf16 v[112:115], v[152:155], v[192:195], v[112:115]
	v_mfma_f32_16x16x32_bf16 v[108:111], v[160:163], v[192:195], v[108:111]
	v_mfma_f32_16x16x32_bf16 v[96:99], v[152:155], v[214:217], v[96:99]
	v_mfma_f32_16x16x32_bf16 v[92:95], v[160:163], v[214:217], v[92:95]
	v_mfma_f32_16x16x32_bf16 v[80:83], v[152:155], v[222:225], v[80:83]
	v_mfma_f32_16x16x32_bf16 v[76:79], v[160:163], v[222:225], v[76:79]
	v_mfma_f32_16x16x32_bf16 v[120:123], v[164:167], v[180:183], v[120:123]
	v_mfma_f32_16x16x32_bf16 v[116:119], v[172:175], v[180:183], v[116:119]
	v_mfma_f32_16x16x32_bf16 v[104:107], v[164:167], v[188:191], v[104:107]
	v_mfma_f32_16x16x32_bf16 v[100:103], v[172:175], v[188:191], v[100:103]
	v_mfma_f32_16x16x32_bf16 v[88:91], v[164:167], v[202:205], v[88:91]
	v_mfma_f32_16x16x32_bf16 v[84:87], v[172:175], v[202:205], v[84:87]
	v_mfma_f32_16x16x32_bf16 v[72:75], v[164:167], v[218:221], v[72:75]
	v_mfma_f32_16x16x32_bf16 v[68:71], v[172:175], v[218:221], v[68:71]
	v_mfma_f32_16x16x32_bf16 v[120:123], v[168:171], v[184:187], v[120:123]
	v_mfma_f32_16x16x32_bf16 v[116:119], v[176:179], v[184:187], v[116:119]
	v_mfma_f32_16x16x32_bf16 v[104:107], v[168:171], v[192:195], v[104:107]
	v_mfma_f32_16x16x32_bf16 v[100:103], v[176:179], v[192:195], v[100:103]
	v_mfma_f32_16x16x32_bf16 v[88:91], v[168:171], v[214:217], v[88:91]
	v_mfma_f32_16x16x32_bf16 v[84:87], v[176:179], v[214:217], v[84:87]
	v_mfma_f32_16x16x32_bf16 v[72:75], v[168:171], v[222:225], v[72:75]
	v_mfma_f32_16x16x32_bf16 v[68:71], v[176:179], v[222:225], v[68:71]
	s_barrier
	s_add_i32 s59, s59, s44
	s_mov_b32 m0, s59
	ds_read_b128 v[180:183], v151 offset:16384
	ds_read_b128 v[184:187], v151 offset:17408
	ds_read_b128 v[188:191], v151 offset:18432
	ds_read_b128 v[192:195], v151 offset:19456
	ds_read_b128 v[202:205], v151 offset:20480
	ds_read_b128 v[214:217], v151 offset:21504
	ds_read_b128 v[218:221], v151 offset:22528
	ds_read_b128 v[222:225], v151 offset:23552
	global_load_lds_dwordx4 v2, s[40:41]
	s_add_i32 m0, s59, 0x2000
	s_add_u32 s60, s40, 0x4000
	s_addc_u32 s61, s41, 0
	s_add_i32 s59, s62, s44
	global_load_lds_dwordx4 v132, s[40:41]
	s_mov_b32 m0, s59
	v_lshl_add_u64 v[228:229], s[42:43], 0, v[134:135]
	global_load_lds_dwordx4 v2, s[60:61]
	s_add_i32 m0, s59, 0x2000
	s_nop 0
	global_load_lds_dwordx4 v132, s[60:61]
	v_lshl_add_u64 v[226:227], s[42:43], 0, v[136:137]
	s_mov_b32 m0, s45
	s_nop 0
	global_load_lds_dwordx4 v136, s[42:43]
	s_mov_b32 m0, s46
	s_nop 0
	global_load_lds_dwordx4 v134, s[42:43]
	s_waitcnt vmcnt(8)
	s_waitcnt lgkmcnt(0)
	s_barrier
	s_waitcnt lgkmcnt(0)
	v_mfma_f32_16x16x32_bf16 v[64:67], v[142:145], v[180:183], v[64:67]
	v_mfma_f32_16x16x32_bf16 v[60:63], v[156:159], v[180:183], v[60:63]
	v_mfma_f32_16x16x32_bf16 v[48:51], v[142:145], v[188:191], v[48:51]
	v_mfma_f32_16x16x32_bf16 v[44:47], v[156:159], v[188:191], v[44:47]
	v_mfma_f32_16x16x32_bf16 v[32:35], v[142:145], v[202:205], v[32:35]
	v_mfma_f32_16x16x32_bf16 v[28:31], v[156:159], v[202:205], v[28:31]
	v_mfma_f32_16x16x32_bf16 v[16:19], v[142:145], v[218:221], v[16:19]
	v_mfma_f32_16x16x32_bf16 v[12:15], v[156:159], v[218:221], v[12:15]
	v_mfma_f32_16x16x32_bf16 v[64:67], v[152:155], v[184:187], v[64:67]
	v_mfma_f32_16x16x32_bf16 v[60:63], v[160:163], v[184:187], v[60:63]
	v_mfma_f32_16x16x32_bf16 v[48:51], v[152:155], v[192:195], v[48:51]
	v_mfma_f32_16x16x32_bf16 v[44:47], v[160:163], v[192:195], v[44:47]
	v_mfma_f32_16x16x32_bf16 v[32:35], v[152:155], v[214:217], v[32:35]
	v_mfma_f32_16x16x32_bf16 v[28:31], v[160:163], v[214:217], v[28:31]
	v_mfma_f32_16x16x32_bf16 v[16:19], v[152:155], v[222:225], v[16:19]
	v_mfma_f32_16x16x32_bf16 v[12:15], v[160:163], v[222:225], v[12:15]
	v_mfma_f32_16x16x32_bf16 v[56:59], v[164:167], v[180:183], v[56:59]
	v_mfma_f32_16x16x32_bf16 v[52:55], v[172:175], v[180:183], v[52:55]
	v_mfma_f32_16x16x32_bf16 v[40:43], v[164:167], v[188:191], v[40:43]
	v_mfma_f32_16x16x32_bf16 v[36:39], v[172:175], v[188:191], v[36:39]
	v_mfma_f32_16x16x32_bf16 v[24:27], v[164:167], v[202:205], v[24:27]
	v_mfma_f32_16x16x32_bf16 v[20:23], v[172:175], v[202:205], v[20:23]
	v_mfma_f32_16x16x32_bf16 v[8:11], v[164:167], v[218:221], v[8:11]
	v_mfma_f32_16x16x32_bf16 v[4:7], v[172:175], v[218:221], v[4:7]
	v_mfma_f32_16x16x32_bf16 v[56:59], v[168:171], v[184:187], v[56:59]
	v_mfma_f32_16x16x32_bf16 v[52:55], v[176:179], v[184:187], v[52:55]
	v_mfma_f32_16x16x32_bf16 v[40:43], v[168:171], v[192:195], v[40:43]
	v_mfma_f32_16x16x32_bf16 v[36:39], v[176:179], v[192:195], v[36:39]
	v_mfma_f32_16x16x32_bf16 v[24:27], v[168:171], v[214:217], v[24:27]
	v_mfma_f32_16x16x32_bf16 v[20:23], v[176:179], v[214:217], v[20:23]
	v_mfma_f32_16x16x32_bf16 v[8:11], v[168:171], v[222:225], v[8:11]
	v_mfma_f32_16x16x32_bf16 v[4:7], v[176:179], v[222:225], v[4:7]
	s_barrier
	s_add_i32 s59, 0, 0x18000
	s_add_i32 s60, 0, 0x1c000
	v_add_u32_e32 v160, s59, v147
	v_add_u32_e32 v176, s60, v147
	ds_read_b128 v[142:145], v160
	ds_read_b128 v[152:155], v160 offset:1024
	ds_read_b128 v[156:159], v160 offset:2048
	ds_read_b128 v[160:163], v160 offset:3072
	ds_read_b128 v[164:167], v176
	ds_read_b128 v[168:171], v176 offset:1024
	ds_read_b128 v[172:175], v176 offset:2048
	ds_read_b128 v[176:179], v176 offset:3072
	s_add_u32 s42, s42, 0x80000
	s_addc_u32 s43, s43, 0
	s_mov_b32 m0, s47
	ds_read_b128 v[180:183], v151 offset:32768
	ds_read_b128 v[184:187], v151 offset:33792
	ds_read_b128 v[188:191], v151 offset:34816
	ds_read_b128 v[192:195], v151 offset:35840
	ds_read_b128 v[202:205], v151 offset:36864
	ds_read_b128 v[214:217], v151 offset:37888
	ds_read_b128 v[218:221], v151 offset:38912
	ds_read_b128 v[222:225], v151 offset:39936
	global_load_lds_dwordx4 v136, s[42:43]
	s_mov_b32 m0, s48
	s_nop 0
	global_load_lds_dwordx4 v134, s[42:43]
	s_waitcnt vmcnt(8)
	s_waitcnt lgkmcnt(0)
	s_barrier
	s_waitcnt lgkmcnt(0)
	v_mfma_f32_16x16x32_bf16 v[128:131], v[142:145], v[180:183], v[128:131]
	v_mfma_f32_16x16x32_bf16 v[124:127], v[156:159], v[180:183], v[124:127]
	v_mfma_f32_16x16x32_bf16 v[112:115], v[142:145], v[188:191], v[112:115]
	v_mfma_f32_16x16x32_bf16 v[108:111], v[156:159], v[188:191], v[108:111]
	v_mfma_f32_16x16x32_bf16 v[96:99], v[142:145], v[202:205], v[96:99]
	v_mfma_f32_16x16x32_bf16 v[92:95], v[156:159], v[202:205], v[92:95]
	v_mfma_f32_16x16x32_bf16 v[80:83], v[142:145], v[218:221], v[80:83]
	v_mfma_f32_16x16x32_bf16 v[76:79], v[156:159], v[218:221], v[76:79]
	v_mfma_f32_16x16x32_bf16 v[128:131], v[152:155], v[184:187], v[128:131]
	v_mfma_f32_16x16x32_bf16 v[124:127], v[160:163], v[184:187], v[124:127]
	v_mfma_f32_16x16x32_bf16 v[112:115], v[152:155], v[192:195], v[112:115]
	v_mfma_f32_16x16x32_bf16 v[108:111], v[160:163], v[192:195], v[108:111]
	v_mfma_f32_16x16x32_bf16 v[96:99], v[152:155], v[214:217], v[96:99]
	v_mfma_f32_16x16x32_bf16 v[92:95], v[160:163], v[214:217], v[92:95]
	v_mfma_f32_16x16x32_bf16 v[80:83], v[152:155], v[222:225], v[80:83]
	v_mfma_f32_16x16x32_bf16 v[76:79], v[160:163], v[222:225], v[76:79]
	v_mfma_f32_16x16x32_bf16 v[120:123], v[164:167], v[180:183], v[120:123]
	v_mfma_f32_16x16x32_bf16 v[116:119], v[172:175], v[180:183], v[116:119]
	v_mfma_f32_16x16x32_bf16 v[104:107], v[164:167], v[188:191], v[104:107]
	v_mfma_f32_16x16x32_bf16 v[100:103], v[172:175], v[188:191], v[100:103]
	v_mfma_f32_16x16x32_bf16 v[88:91], v[164:167], v[202:205], v[88:91]
	v_mfma_f32_16x16x32_bf16 v[84:87], v[172:175], v[202:205], v[84:87]
	v_mfma_f32_16x16x32_bf16 v[72:75], v[164:167], v[218:221], v[72:75]
	v_mfma_f32_16x16x32_bf16 v[68:71], v[172:175], v[218:221], v[68:71]
	v_mfma_f32_16x16x32_bf16 v[120:123], v[168:171], v[184:187], v[120:123]
	v_mfma_f32_16x16x32_bf16 v[116:119], v[176:179], v[184:187], v[116:119]
	v_mfma_f32_16x16x32_bf16 v[104:107], v[168:171], v[192:195], v[104:107]
	v_mfma_f32_16x16x32_bf16 v[100:103], v[176:179], v[192:195], v[100:103]
	v_mfma_f32_16x16x32_bf16 v[88:91], v[168:171], v[214:217], v[88:91]
	v_mfma_f32_16x16x32_bf16 v[84:87], v[176:179], v[214:217], v[84:87]
	v_mfma_f32_16x16x32_bf16 v[72:75], v[168:171], v[222:225], v[72:75]
	v_mfma_f32_16x16x32_bf16 v[68:71], v[176:179], v[222:225], v[68:71]
	s_barrier
	s_add_u32 s42, s40, 0x8000
	s_addc_u32 s43, s41, 0
	s_add_i32 s59, s59, s44
	s_mov_b32 m0, s59
	ds_read_b128 v[180:183], v151 offset:49152
	ds_read_b128 v[184:187], v151 offset:50176
	ds_read_b128 v[188:191], v151 offset:51200
	ds_read_b128 v[192:195], v151 offset:52224
	ds_read_b128 v[202:205], v151 offset:53248
	ds_read_b128 v[214:217], v151 offset:54272
	ds_read_b128 v[218:221], v151 offset:55296
	ds_read_b128 v[222:225], v151 offset:56320
	global_load_lds_dwordx4 v2, s[42:43]
	s_add_i32 m0, s59, 0x2000
	s_add_u32 s40, s40, 0xc000
	v_lshl_add_u64 v[230:231], s[42:43], 0, v[132:133]
	s_addc_u32 s41, s41, 0
	s_add_i32 s42, s60, s44
	global_load_lds_dwordx4 v[230:231], off
	s_mov_b32 m0, s42
	v_lshl_add_u64 v[226:227], v[226:227], 0, s[4:5]
	global_load_lds_dwordx4 v2, s[40:41]
	s_add_i32 m0, s42, 0x2000
	s_nop 0
	global_load_lds_dwordx4 v132, s[40:41]
	s_mov_b32 m0, s49
	s_nop 0
	global_load_lds_dwordx4 v[226:227], off
	v_lshl_add_u64 v[226:227], v[228:229], 0, s[4:5]
	s_mov_b32 m0, s50
	s_nop 0
	global_load_lds_dwordx4 v[226:227], off
	s_waitcnt vmcnt(8)
	s_waitcnt lgkmcnt(0)
	s_barrier
	s_waitcnt lgkmcnt(0)
	v_mfma_f32_16x16x32_bf16 v[64:67], v[142:145], v[180:183], v[64:67]
	v_mfma_f32_16x16x32_bf16 v[60:63], v[156:159], v[180:183], v[60:63]
	v_mfma_f32_16x16x32_bf16 v[48:51], v[142:145], v[188:191], v[48:51]
	v_mfma_f32_16x16x32_bf16 v[44:47], v[156:159], v[188:191], v[44:47]
	v_mfma_f32_16x16x32_bf16 v[32:35], v[142:145], v[202:205], v[32:35]
	v_mfma_f32_16x16x32_bf16 v[28:31], v[156:159], v[202:205], v[28:31]
	v_mfma_f32_16x16x32_bf16 v[16:19], v[142:145], v[218:221], v[16:19]
	v_mfma_f32_16x16x32_bf16 v[12:15], v[156:159], v[218:221], v[12:15]
	v_mfma_f32_16x16x32_bf16 v[64:67], v[152:155], v[184:187], v[64:67]
	v_mfma_f32_16x16x32_bf16 v[60:63], v[160:163], v[184:187], v[60:63]
	v_mfma_f32_16x16x32_bf16 v[48:51], v[152:155], v[192:195], v[48:51]
	v_mfma_f32_16x16x32_bf16 v[44:47], v[160:163], v[192:195], v[44:47]
	v_mfma_f32_16x16x32_bf16 v[32:35], v[152:155], v[214:217], v[32:35]
	v_mfma_f32_16x16x32_bf16 v[28:31], v[160:163], v[214:217], v[28:31]
	v_mfma_f32_16x16x32_bf16 v[16:19], v[152:155], v[222:225], v[16:19]
	v_mfma_f32_16x16x32_bf16 v[12:15], v[160:163], v[222:225], v[12:15]
	v_mfma_f32_16x16x32_bf16 v[56:59], v[164:167], v[180:183], v[56:59]
	v_mfma_f32_16x16x32_bf16 v[52:55], v[172:175], v[180:183], v[52:55]
	v_mfma_f32_16x16x32_bf16 v[40:43], v[164:167], v[188:191], v[40:43]
	v_mfma_f32_16x16x32_bf16 v[36:39], v[172:175], v[188:191], v[36:39]
	v_mfma_f32_16x16x32_bf16 v[24:27], v[164:167], v[202:205], v[24:27]
	v_mfma_f32_16x16x32_bf16 v[20:23], v[172:175], v[202:205], v[20:23]
	v_mfma_f32_16x16x32_bf16 v[8:11], v[164:167], v[218:221], v[8:11]
	v_mfma_f32_16x16x32_bf16 v[4:7], v[172:175], v[218:221], v[4:7]
	v_mfma_f32_16x16x32_bf16 v[56:59], v[168:171], v[184:187], v[56:59]
	v_mfma_f32_16x16x32_bf16 v[52:55], v[176:179], v[184:187], v[52:55]
	v_mfma_f32_16x16x32_bf16 v[40:43], v[168:171], v[192:195], v[40:43]
	v_mfma_f32_16x16x32_bf16 v[36:39], v[176:179], v[192:195], v[36:39]
	v_mfma_f32_16x16x32_bf16 v[24:27], v[168:171], v[214:217], v[24:27]
	v_mfma_f32_16x16x32_bf16 v[20:23], v[176:179], v[214:217], v[20:23]
	v_mfma_f32_16x16x32_bf16 v[8:11], v[168:171], v[222:225], v[8:11]
	v_mfma_f32_16x16x32_bf16 v[4:7], v[176:179], v[222:225], v[4:7]
	s_barrier
	s_add_i32 s58, s58, 2
	s_add_u32 s56, s56, 0x10000
	s_addc_u32 s57, s57, 0
	s_add_u32 s34, s34, 0x100
	s_addc_u32 s35, s35, 0
	s_cmp_gt_u32 s58, 29
	s_cbranch_scc0 .LBB0_326
	s_and_b64 vcc, exec, s[6:7]
	s_cbranch_vccz .LBB0_329
	s_barrier

.LBB0_366:
	s_add_u32 s6, s0, 0xfff80080
	s_addc_u32 s7, s1, -1
	s_add_i32 s62, 0, 0x10000
	s_cmp_eq_u32 s61, 28
	s_cselect_b32 s9, s43, s7
	s_cselect_b32 s8, s51, s6
	v_add_u32_e32 v146, s62, v150
	s_cselect_b32 s7, s49, s60
	s_cselect_b32 s6, s58, s59
	s_add_i32 s64, 0, 0x14000
	ds_read_b128 v[142:145], v146
	ds_read_b128 v[156:159], v146 offset:1024
	ds_read_b128 v[160:163], v146 offset:2048
	ds_read_b128 v[164:167], v146 offset:3072
	v_add_u32_e32 v146, s64, v150
	ds_read_b128 v[168:171], v146
	ds_read_b128 v[172:175], v146 offset:1024
	ds_read_b128 v[176:179], v146 offset:2048
	ds_read_b128 v[180:183], v146 offset:3072
	s_add_i32 m0, s13, 0xc000
	ds_read_b128 v[184:187], v154
	ds_read_b128 v[188:191], v154 offset:1024
	ds_read_b128 v[192:195], v154 offset:2048
	ds_read_b128 v[202:205], v154 offset:3072
	ds_read_b128 v[214:217], v154 offset:4096
	ds_read_b128 v[218:221], v154 offset:5120
	ds_read_b128 v[222:225], v154 offset:6144
	ds_read_b128 v[226:229], v154 offset:7168
	global_load_lds_dwordx4 v138, s[0:1]
	s_add_i32 m0, s13, 0xe000
	s_nop 0
	global_load_lds_dwordx4 v140, s[0:1]
	s_waitcnt vmcnt(8)
	s_waitcnt lgkmcnt(0)
	s_barrier
	s_waitcnt lgkmcnt(0)
	v_mfma_f32_16x16x32_bf16 v[128:131], v[142:145], v[184:187], v[128:131]
	v_mfma_f32_16x16x32_bf16 v[124:127], v[160:163], v[184:187], v[124:127]
	v_mfma_f32_16x16x32_bf16 v[112:115], v[142:145], v[192:195], v[112:115]
	v_mfma_f32_16x16x32_bf16 v[108:111], v[160:163], v[192:195], v[108:111]
	v_mfma_f32_16x16x32_bf16 v[96:99], v[142:145], v[214:217], v[96:99]
	v_mfma_f32_16x16x32_bf16 v[92:95], v[160:163], v[214:217], v[92:95]
	v_mfma_f32_16x16x32_bf16 v[80:83], v[142:145], v[222:225], v[80:83]
	v_mfma_f32_16x16x32_bf16 v[76:79], v[160:163], v[222:225], v[76:79]
	v_mfma_f32_16x16x32_bf16 v[128:131], v[156:159], v[188:191], v[128:131]
	v_mfma_f32_16x16x32_bf16 v[124:127], v[164:167], v[188:191], v[124:127]
	v_mfma_f32_16x16x32_bf16 v[112:115], v[156:159], v[202:205], v[112:115]
	v_mfma_f32_16x16x32_bf16 v[108:111], v[164:167], v[202:205], v[108:111]
	v_mfma_f32_16x16x32_bf16 v[96:99], v[156:159], v[218:221], v[96:99]
	v_mfma_f32_16x16x32_bf16 v[92:95], v[164:167], v[218:221], v[92:95]
	v_mfma_f32_16x16x32_bf16 v[80:83], v[156:159], v[226:229], v[80:83]
	v_mfma_f32_16x16x32_bf16 v[76:79], v[164:167], v[226:229], v[76:79]
	v_mfma_f32_16x16x32_bf16 v[120:123], v[168:171], v[184:187], v[120:123]
	v_mfma_f32_16x16x32_bf16 v[116:119], v[176:179], v[184:187], v[116:119]
	v_mfma_f32_16x16x32_bf16 v[104:107], v[168:171], v[192:195], v[104:107]
	v_mfma_f32_16x16x32_bf16 v[100:103], v[176:179], v[192:195], v[100:103]
	v_mfma_f32_16x16x32_bf16 v[88:91], v[168:171], v[214:217], v[88:91]
	v_mfma_f32_16x16x32_bf16 v[84:87], v[176:179], v[214:217], v[84:87]
	v_mfma_f32_16x16x32_bf16 v[72:75], v[168:171], v[222:225], v[72:75]
	v_mfma_f32_16x16x32_bf16 v[68:71], v[176:179], v[222:225], v[68:71]
	v_mfma_f32_16x16x32_bf16 v[120:123], v[172:175], v[188:191], v[120:123]
	v_mfma_f32_16x16x32_bf16 v[116:119], v[180:183], v[188:191], v[116:119]
	v_mfma_f32_16x16x32_bf16 v[104:107], v[172:175], v[202:205], v[104:107]
	v_mfma_f32_16x16x32_bf16 v[100:103], v[180:183], v[202:205], v[100:103]
	v_mfma_f32_16x16x32_bf16 v[88:91], v[172:175], v[218:221], v[88:91]
	v_mfma_f32_16x16x32_bf16 v[84:87], v[180:183], v[218:221], v[84:87]
	v_mfma_f32_16x16x32_bf16 v[72:75], v[172:175], v[226:229], v[72:75]
	v_mfma_f32_16x16x32_bf16 v[68:71], v[180:183], v[226:229], v[68:71]
	s_barrier
	s_add_i32 s62, s62, s12
	s_mov_b32 m0, s62
	ds_read_b128 v[184:187], v154 offset:16384
	ds_read_b128 v[188:191], v154 offset:17408
	ds_read_b128 v[192:195], v154 offset:18432
	ds_read_b128 v[202:205], v154 offset:19456
	ds_read_b128 v[214:217], v154 offset:20480
	ds_read_b128 v[218:221], v154 offset:21504
	ds_read_b128 v[222:225], v154 offset:22528
	ds_read_b128 v[226:229], v154 offset:23552
	global_load_lds_dwordx4 v2, s[6:7]
	s_add_i32 m0, s62, 0x2000
	s_add_u32 s62, s6, 0x4000
	s_addc_u32 s63, s7, 0
	s_add_i32 s64, s64, s12
	global_load_lds_dwordx4 v132, s[6:7]
	s_mov_b32 m0, s64
	v_lshl_add_u64 v[230:231], s[8:9], 0, v[134:135]
	global_load_lds_dwordx4 v2, s[62:63]
	s_add_i32 m0, s64, 0x2000
	s_nop 0
	global_load_lds_dwordx4 v132, s[62:63]
	v_lshl_add_u64 v[146:147], s[8:9], 0, v[136:137]
	s_mov_b32 m0, s13
	s_nop 0
	global_load_lds_dwordx4 v136, s[8:9]
	s_mov_b32 m0, s14
	s_nop 0
	global_load_lds_dwordx4 v134, s[8:9]
	s_waitcnt vmcnt(8)
	s_waitcnt lgkmcnt(0)
	s_barrier
	s_waitcnt lgkmcnt(0)
	v_mfma_f32_16x16x32_bf16 v[64:67], v[142:145], v[184:187], v[64:67]
	v_mfma_f32_16x16x32_bf16 v[60:63], v[160:163], v[184:187], v[60:63]
	v_mfma_f32_16x16x32_bf16 v[48:51], v[142:145], v[192:195], v[48:51]
	v_mfma_f32_16x16x32_bf16 v[44:47], v[160:163], v[192:195], v[44:47]
	v_mfma_f32_16x16x32_bf16 v[32:35], v[142:145], v[214:217], v[32:35]
	v_mfma_f32_16x16x32_bf16 v[28:31], v[160:163], v[214:217], v[28:31]
	v_mfma_f32_16x16x32_bf16 v[16:19], v[142:145], v[222:225], v[16:19]
	v_mfma_f32_16x16x32_bf16 v[12:15], v[160:163], v[222:225], v[12:15]
	v_mfma_f32_16x16x32_bf16 v[64:67], v[156:159], v[188:191], v[64:67]
	v_mfma_f32_16x16x32_bf16 v[60:63], v[164:167], v[188:191], v[60:63]
	v_mfma_f32_16x16x32_bf16 v[48:51], v[156:159], v[202:205], v[48:51]
	v_mfma_f32_16x16x32_bf16 v[44:47], v[164:167], v[202:205], v[44:47]
	v_mfma_f32_16x16x32_bf16 v[32:35], v[156:159], v[218:221], v[32:35]
	v_mfma_f32_16x16x32_bf16 v[28:31], v[164:167], v[218:221], v[28:31]
	v_mfma_f32_16x16x32_bf16 v[16:19], v[156:159], v[226:229], v[16:19]
	v_mfma_f32_16x16x32_bf16 v[12:15], v[164:167], v[226:229], v[12:15]
	v_mfma_f32_16x16x32_bf16 v[56:59], v[168:171], v[184:187], v[56:59]
	v_mfma_f32_16x16x32_bf16 v[52:55], v[176:179], v[184:187], v[52:55]
	v_mfma_f32_16x16x32_bf16 v[40:43], v[168:171], v[192:195], v[40:43]
	v_mfma_f32_16x16x32_bf16 v[36:39], v[176:179], v[192:195], v[36:39]
	v_mfma_f32_16x16x32_bf16 v[24:27], v[168:171], v[214:217], v[24:27]
	v_mfma_f32_16x16x32_bf16 v[20:23], v[176:179], v[214:217], v[20:23]
	v_mfma_f32_16x16x32_bf16 v[8:11], v[168:171], v[222:225], v[8:11]
	v_mfma_f32_16x16x32_bf16 v[4:7], v[176:179], v[222:225], v[4:7]
	v_mfma_f32_16x16x32_bf16 v[56:59], v[172:175], v[188:191], v[56:59]
	v_mfma_f32_16x16x32_bf16 v[52:55], v[180:183], v[188:191], v[52:55]
	v_mfma_f32_16x16x32_bf16 v[40:43], v[172:175], v[202:205], v[40:43]
	v_mfma_f32_16x16x32_bf16 v[36:39], v[180:183], v[202:205], v[36:39]
	v_mfma_f32_16x16x32_bf16 v[24:27], v[172:175], v[218:221], v[24:27]
	v_mfma_f32_16x16x32_bf16 v[20:23], v[180:183], v[218:221], v[20:23]
	v_mfma_f32_16x16x32_bf16 v[8:11], v[172:175], v[226:229], v[8:11]
	v_mfma_f32_16x16x32_bf16 v[4:7], v[180:183], v[226:229], v[4:7]
	s_barrier
	s_add_i32 s62, 0, 0x18000
	v_add_u32_e32 v148, s62, v150
	s_add_i32 s63, 0, 0x1c000
	ds_read_b128 v[142:145], v148
	ds_read_b128 v[156:159], v148 offset:1024
	ds_read_b128 v[160:163], v148 offset:2048
	ds_read_b128 v[164:167], v148 offset:3072
	v_add_u32_e32 v148, s63, v150
	ds_read_b128 v[168:171], v148
	ds_read_b128 v[172:175], v148 offset:1024
	ds_read_b128 v[176:179], v148 offset:2048
	ds_read_b128 v[180:183], v148 offset:3072
	s_add_u32 s8, s8, 0x80000
	s_addc_u32 s9, s9, 0
	s_mov_b32 m0, s15
	ds_read_b128 v[184:187], v154 offset:32768
	ds_read_b128 v[188:191], v154 offset:33792
	ds_read_b128 v[192:195], v154 offset:34816
	ds_read_b128 v[202:205], v154 offset:35840
	ds_read_b128 v[214:217], v154 offset:36864
	ds_read_b128 v[218:221], v154 offset:37888
	ds_read_b128 v[222:225], v154 offset:38912
	ds_read_b128 v[226:229], v154 offset:39936
	global_load_lds_dwordx4 v136, s[8:9]
	s_mov_b32 m0, s22
	s_nop 0
	global_load_lds_dwordx4 v134, s[8:9]
	s_waitcnt vmcnt(8)
	s_waitcnt lgkmcnt(0)
	s_barrier
	s_waitcnt lgkmcnt(0)
	v_mfma_f32_16x16x32_bf16 v[128:131], v[142:145], v[184:187], v[128:131]
	v_mfma_f32_16x16x32_bf16 v[124:127], v[160:163], v[184:187], v[124:127]
	v_mfma_f32_16x16x32_bf16 v[112:115], v[142:145], v[192:195], v[112:115]
	v_mfma_f32_16x16x32_bf16 v[108:111], v[160:163], v[192:195], v[108:111]
	v_mfma_f32_16x16x32_bf16 v[96:99], v[142:145], v[214:217], v[96:99]
	v_mfma_f32_16x16x32_bf16 v[92:95], v[160:163], v[214:217], v[92:95]
	v_mfma_f32_16x16x32_bf16 v[80:83], v[142:145], v[222:225], v[80:83]
	v_mfma_f32_16x16x32_bf16 v[76:79], v[160:163], v[222:225], v[76:79]
	v_mfma_f32_16x16x32_bf16 v[128:131], v[156:159], v[188:191], v[128:131]
	v_mfma_f32_16x16x32_bf16 v[124:127], v[164:167], v[188:191], v[124:127]
	v_mfma_f32_16x16x32_bf16 v[112:115], v[156:159], v[202:205], v[112:115]
	v_mfma_f32_16x16x32_bf16 v[108:111], v[164:167], v[202:205], v[108:111]
	v_mfma_f32_16x16x32_bf16 v[96:99], v[156:159], v[218:221], v[96:99]
	v_mfma_f32_16x16x32_bf16 v[92:95], v[164:167], v[218:221], v[92:95]
	v_mfma_f32_16x16x32_bf16 v[80:83], v[156:159], v[226:229], v[80:83]
	v_mfma_f32_16x16x32_bf16 v[76:79], v[164:167], v[226:229], v[76:79]
	v_mfma_f32_16x16x32_bf16 v[120:123], v[168:171], v[184:187], v[120:123]
	v_mfma_f32_16x16x32_bf16 v[116:119], v[176:179], v[184:187], v[116:119]
	v_mfma_f32_16x16x32_bf16 v[104:107], v[168:171], v[192:195], v[104:107]
	v_mfma_f32_16x16x32_bf16 v[100:103], v[176:179], v[192:195], v[100:103]
	v_mfma_f32_16x16x32_bf16 v[88:91], v[168:171], v[214:217], v[88:91]
	v_mfma_f32_16x16x32_bf16 v[84:87], v[176:179], v[214:217], v[84:87]
	v_mfma_f32_16x16x32_bf16 v[72:75], v[168:171], v[222:225], v[72:75]
	v_mfma_f32_16x16x32_bf16 v[68:71], v[176:179], v[222:225], v[68:71]
	v_mfma_f32_16x16x32_bf16 v[120:123], v[172:175], v[188:191], v[120:123]
	v_mfma_f32_16x16x32_bf16 v[116:119], v[180:183], v[188:191], v[116:119]
	v_mfma_f32_16x16x32_bf16 v[104:107], v[172:175], v[202:205], v[104:107]
	v_mfma_f32_16x16x32_bf16 v[100:103], v[180:183], v[202:205], v[100:103]
	v_mfma_f32_16x16x32_bf16 v[88:91], v[172:175], v[218:221], v[88:91]
	v_mfma_f32_16x16x32_bf16 v[84:87], v[180:183], v[218:221], v[84:87]
	v_mfma_f32_16x16x32_bf16 v[72:75], v[172:175], v[226:229], v[72:75]
	v_mfma_f32_16x16x32_bf16 v[68:71], v[180:183], v[226:229], v[68:71]
	s_barrier
	s_add_u32 s8, s6, 0x8000
	s_addc_u32 s9, s7, 0
	s_add_i32 s62, s62, s12
	s_mov_b32 m0, s62
	ds_read_b128 v[184:187], v154 offset:49152
	ds_read_b128 v[188:191], v154 offset:50176
	ds_read_b128 v[192:195], v154 offset:51200
	ds_read_b128 v[202:205], v154 offset:52224
	ds_read_b128 v[214:217], v154 offset:53248
	ds_read_b128 v[218:221], v154 offset:54272
	ds_read_b128 v[222:225], v154 offset:55296
	ds_read_b128 v[226:229], v154 offset:56320
	global_load_lds_dwordx4 v2, s[8:9]
	s_add_i32 m0, s62, 0x2000
	s_add_u32 s6, s6, 0xc000
	v_lshl_add_u64 v[232:233], s[8:9], 0, v[132:133]
	s_addc_u32 s7, s7, 0
	s_add_i32 s8, s63, s12
	global_load_lds_dwordx4 v[232:233], off
	s_mov_b32 m0, s8
	v_lshl_add_u64 v[146:147], v[146:147], 0, s[4:5]
	global_load_lds_dwordx4 v2, s[6:7]
	s_add_i32 m0, s8, 0x2000
	s_nop 0
	global_load_lds_dwordx4 v132, s[6:7]
	s_mov_b32 m0, s34
	s_nop 0
	global_load_lds_dwordx4 v[146:147], off
	v_lshl_add_u64 v[146:147], v[230:231], 0, s[4:5]
	s_mov_b32 m0, s35
	s_nop 0
	global_load_lds_dwordx4 v[146:147], off
	s_waitcnt vmcnt(8)
	s_waitcnt lgkmcnt(0)
	s_barrier
	s_waitcnt lgkmcnt(0)
	v_mfma_f32_16x16x32_bf16 v[64:67], v[142:145], v[184:187], v[64:67]
	v_mfma_f32_16x16x32_bf16 v[60:63], v[160:163], v[184:187], v[60:63]
	v_mfma_f32_16x16x32_bf16 v[48:51], v[142:145], v[192:195], v[48:51]
	v_mfma_f32_16x16x32_bf16 v[44:47], v[160:163], v[192:195], v[44:47]
	v_mfma_f32_16x16x32_bf16 v[32:35], v[142:145], v[214:217], v[32:35]
	v_mfma_f32_16x16x32_bf16 v[28:31], v[160:163], v[214:217], v[28:31]
	v_mfma_f32_16x16x32_bf16 v[16:19], v[142:145], v[222:225], v[16:19]
	v_mfma_f32_16x16x32_bf16 v[12:15], v[160:163], v[222:225], v[12:15]
	v_mfma_f32_16x16x32_bf16 v[64:67], v[156:159], v[188:191], v[64:67]
	v_mfma_f32_16x16x32_bf16 v[60:63], v[164:167], v[188:191], v[60:63]
	v_mfma_f32_16x16x32_bf16 v[48:51], v[156:159], v[202:205], v[48:51]
	v_mfma_f32_16x16x32_bf16 v[44:47], v[164:167], v[202:205], v[44:47]
	v_mfma_f32_16x16x32_bf16 v[32:35], v[156:159], v[218:221], v[32:35]
	v_mfma_f32_16x16x32_bf16 v[28:31], v[164:167], v[218:221], v[28:31]
	v_mfma_f32_16x16x32_bf16 v[16:19], v[156:159], v[226:229], v[16:19]
	v_mfma_f32_16x16x32_bf16 v[12:15], v[164:167], v[226:229], v[12:15]
	v_mfma_f32_16x16x32_bf16 v[56:59], v[168:171], v[184:187], v[56:59]
	v_mfma_f32_16x16x32_bf16 v[52:55], v[176:179], v[184:187], v[52:55]
	v_mfma_f32_16x16x32_bf16 v[40:43], v[168:171], v[192:195], v[40:43]
	v_mfma_f32_16x16x32_bf16 v[36:39], v[176:179], v[192:195], v[36:39]
	v_mfma_f32_16x16x32_bf16 v[24:27], v[168:171], v[214:217], v[24:27]
	v_mfma_f32_16x16x32_bf16 v[20:23], v[176:179], v[214:217], v[20:23]
	v_mfma_f32_16x16x32_bf16 v[8:11], v[168:171], v[222:225], v[8:11]
	v_mfma_f32_16x16x32_bf16 v[4:7], v[176:179], v[222:225], v[4:7]
	v_mfma_f32_16x16x32_bf16 v[56:59], v[172:175], v[188:191], v[56:59]
	v_mfma_f32_16x16x32_bf16 v[52:55], v[180:183], v[188:191], v[52:55]
	v_mfma_f32_16x16x32_bf16 v[40:43], v[172:175], v[202:205], v[40:43]
	v_mfma_f32_16x16x32_bf16 v[36:39], v[180:183], v[202:205], v[36:39]
	v_mfma_f32_16x16x32_bf16 v[24:27], v[172:175], v[218:221], v[24:27]
	v_mfma_f32_16x16x32_bf16 v[20:23], v[180:183], v[218:221], v[20:23]
	v_mfma_f32_16x16x32_bf16 v[8:11], v[172:175], v[226:229], v[8:11]
	v_mfma_f32_16x16x32_bf16 v[4:7], v[180:183], v[226:229], v[4:7]
	s_barrier
	s_add_i32 s61, s61, 2
	s_add_u32 s59, s59, 0x10000
	s_addc_u32 s60, s60, 0
	s_add_u32 s0, s0, 0x100
	s_addc_u32 s1, s1, 0
	s_cmp_gt_u32 s61, 29
	s_cbranch_scc0 .LBB0_366
	s_and_b64 vcc, exec, s[46:47]
	s_cbranch_vccz .LBB0_369
	s_barrier

.LBB0_733:
	s_add_u32 s48, s34, 0xfff80080
	s_addc_u32 s49, s35, -1
	s_add_i32 s69, 0, 0x10000
	s_cmp_eq_u32 s68, 28
	s_cselect_b32 s51, s13, s49
	s_cselect_b32 s50, s64, s48
	s_cselect_b32 s49, s9, s67
	s_cselect_b32 s48, s65, s66
	s_add_i32 s72, 0, 0x14000
	v_add_u32_e32 v136, s69, v204
	v_add_u32_e32 v160, s72, v204
	ds_read_b128 v[116:119], v136
	ds_read_b128 v[128:131], v136 offset:1024
	ds_read_b128 v[132:135], v136 offset:2048
	ds_read_b128 v[136:139], v136 offset:3072
	ds_read_b128 v[140:143], v160
	ds_read_b128 v[148:151], v160 offset:1024
	ds_read_b128 v[152:155], v160 offset:2048
	ds_read_b128 v[160:163], v160 offset:3072
	s_add_i32 m0, s55, 0xc000
	ds_read_b128 v[164:167], v244
	ds_read_b128 v[168:171], v244 offset:1024
	ds_read_b128 v[172:175], v244 offset:2048
	ds_read_b128 v[176:179], v244 offset:3072
	ds_read_b128 v[180:183], v244 offset:4096
	ds_read_b128 v[184:187], v244 offset:5120
	ds_read_b128 v[188:191], v244 offset:6144
	ds_read_b128 v[192:195], v244 offset:7168
	global_load_lds_dwordx4 v218, s[34:35]
	s_add_i32 m0, s55, 0xe000
	s_nop 0
	global_load_lds_dwordx4 v220, s[34:35]
	s_waitcnt vmcnt(8)
	s_waitcnt lgkmcnt(0)
	s_barrier
	s_waitcnt lgkmcnt(0)
	v_mfma_f32_16x16x32_bf16 v[156:159], v[116:119], v[164:167], v[156:159]
	v_mfma_f32_16x16x32_bf16 v[144:147], v[132:135], v[164:167], v[144:147]
	v_mfma_f32_16x16x32_bf16 v[112:115], v[116:119], v[172:175], v[112:115]
	v_mfma_f32_16x16x32_bf16 v[108:111], v[132:135], v[172:175], v[108:111]
	v_mfma_f32_16x16x32_bf16 v[96:99], v[116:119], v[180:183], v[96:99]
	v_mfma_f32_16x16x32_bf16 v[92:95], v[132:135], v[180:183], v[92:95]
	v_mfma_f32_16x16x32_bf16 v[80:83], v[116:119], v[188:191], v[80:83]
	v_mfma_f32_16x16x32_bf16 v[76:79], v[132:135], v[188:191], v[76:79]
	v_mfma_f32_16x16x32_bf16 v[156:159], v[128:131], v[168:171], v[156:159]
	v_mfma_f32_16x16x32_bf16 v[144:147], v[136:139], v[168:171], v[144:147]
	v_mfma_f32_16x16x32_bf16 v[112:115], v[128:131], v[176:179], v[112:115]
	v_mfma_f32_16x16x32_bf16 v[108:111], v[136:139], v[176:179], v[108:111]
	v_mfma_f32_16x16x32_bf16 v[96:99], v[128:131], v[184:187], v[96:99]
	v_mfma_f32_16x16x32_bf16 v[92:95], v[136:139], v[184:187], v[92:95]
	v_mfma_f32_16x16x32_bf16 v[80:83], v[128:131], v[192:195], v[80:83]
	v_mfma_f32_16x16x32_bf16 v[76:79], v[136:139], v[192:195], v[76:79]
	v_mfma_f32_16x16x32_bf16 v[124:127], v[140:143], v[164:167], v[124:127]
	v_mfma_f32_16x16x32_bf16 v[120:123], v[152:155], v[164:167], v[120:123]
	v_mfma_f32_16x16x32_bf16 v[104:107], v[140:143], v[172:175], v[104:107]
	v_mfma_f32_16x16x32_bf16 v[100:103], v[152:155], v[172:175], v[100:103]
	v_mfma_f32_16x16x32_bf16 v[88:91], v[140:143], v[180:183], v[88:91]
	v_mfma_f32_16x16x32_bf16 v[84:87], v[152:155], v[180:183], v[84:87]
	v_mfma_f32_16x16x32_bf16 v[72:75], v[140:143], v[188:191], v[72:75]
	v_mfma_f32_16x16x32_bf16 v[68:71], v[152:155], v[188:191], v[68:71]
	v_mfma_f32_16x16x32_bf16 v[124:127], v[148:151], v[168:171], v[124:127]
	v_mfma_f32_16x16x32_bf16 v[120:123], v[160:163], v[168:171], v[120:123]
	v_mfma_f32_16x16x32_bf16 v[104:107], v[148:151], v[176:179], v[104:107]
	v_mfma_f32_16x16x32_bf16 v[100:103], v[160:163], v[176:179], v[100:103]
	v_mfma_f32_16x16x32_bf16 v[88:91], v[148:151], v[184:187], v[88:91]
	v_mfma_f32_16x16x32_bf16 v[84:87], v[160:163], v[184:187], v[84:87]
	v_mfma_f32_16x16x32_bf16 v[72:75], v[148:151], v[192:195], v[72:75]
	v_mfma_f32_16x16x32_bf16 v[68:71], v[160:163], v[192:195], v[68:71]
	s_barrier
	s_add_i32 s69, s69, s52
	s_mov_b32 m0, s69
	ds_read_b128 v[164:167], v244 offset:16384
	ds_read_b128 v[168:171], v244 offset:17408
	ds_read_b128 v[172:175], v244 offset:18432
	ds_read_b128 v[176:179], v244 offset:19456
	ds_read_b128 v[180:183], v244 offset:20480
	ds_read_b128 v[184:187], v244 offset:21504
	ds_read_b128 v[188:191], v244 offset:22528
	ds_read_b128 v[192:195], v244 offset:23552
	global_load_lds_dwordx4 v2, s[48:49]
	s_add_i32 m0, s69, 0x2000
	s_add_u32 s70, s48, 0x4000
	s_addc_u32 s71, s49, 0
	s_add_i32 s69, s72, s52
	global_load_lds_dwordx4 v196, s[48:49]
	s_mov_b32 m0, s69
	v_lshl_add_u64 v[224:225], s[50:51], 0, v[214:215]
	global_load_lds_dwordx4 v2, s[70:71]
	s_add_i32 m0, s69, 0x2000
	s_nop 0
	global_load_lds_dwordx4 v196, s[70:71]
	v_lshl_add_u64 v[222:223], s[50:51], 0, v[216:217]
	s_mov_b32 m0, s55
	s_nop 0
	global_load_lds_dwordx4 v216, s[50:51]
	s_mov_b32 m0, s56
	s_nop 0
	global_load_lds_dwordx4 v214, s[50:51]
	s_waitcnt vmcnt(8)
	s_waitcnt lgkmcnt(0)
	s_barrier
	s_waitcnt lgkmcnt(0)
	v_mfma_f32_16x16x32_bf16 v[64:67], v[116:119], v[164:167], v[64:67]
	v_mfma_f32_16x16x32_bf16 v[60:63], v[132:135], v[164:167], v[60:63]
	v_mfma_f32_16x16x32_bf16 v[48:51], v[116:119], v[172:175], v[48:51]
	v_mfma_f32_16x16x32_bf16 v[44:47], v[132:135], v[172:175], v[44:47]
	v_mfma_f32_16x16x32_bf16 v[32:35], v[116:119], v[180:183], v[32:35]
	v_mfma_f32_16x16x32_bf16 v[28:31], v[132:135], v[180:183], v[28:31]
	v_mfma_f32_16x16x32_bf16 v[16:19], v[116:119], v[188:191], v[16:19]
	v_mfma_f32_16x16x32_bf16 v[12:15], v[132:135], v[188:191], v[12:15]
	v_mfma_f32_16x16x32_bf16 v[64:67], v[128:131], v[168:171], v[64:67]
	v_mfma_f32_16x16x32_bf16 v[60:63], v[136:139], v[168:171], v[60:63]
	v_mfma_f32_16x16x32_bf16 v[48:51], v[128:131], v[176:179], v[48:51]
	v_mfma_f32_16x16x32_bf16 v[44:47], v[136:139], v[176:179], v[44:47]
	v_mfma_f32_16x16x32_bf16 v[32:35], v[128:131], v[184:187], v[32:35]
	v_mfma_f32_16x16x32_bf16 v[28:31], v[136:139], v[184:187], v[28:31]
	v_mfma_f32_16x16x32_bf16 v[16:19], v[128:131], v[192:195], v[16:19]
	v_mfma_f32_16x16x32_bf16 v[12:15], v[136:139], v[192:195], v[12:15]
	v_mfma_f32_16x16x32_bf16 v[56:59], v[140:143], v[164:167], v[56:59]
	v_mfma_f32_16x16x32_bf16 v[52:55], v[152:155], v[164:167], v[52:55]
	v_mfma_f32_16x16x32_bf16 v[40:43], v[140:143], v[172:175], v[40:43]
	v_mfma_f32_16x16x32_bf16 v[36:39], v[152:155], v[172:175], v[36:39]
	v_mfma_f32_16x16x32_bf16 v[24:27], v[140:143], v[180:183], v[24:27]
	v_mfma_f32_16x16x32_bf16 v[20:23], v[152:155], v[180:183], v[20:23]
	v_mfma_f32_16x16x32_bf16 v[8:11], v[140:143], v[188:191], v[8:11]
	v_mfma_f32_16x16x32_bf16 v[4:7], v[152:155], v[188:191], v[4:7]
	v_mfma_f32_16x16x32_bf16 v[56:59], v[148:151], v[168:171], v[56:59]
	v_mfma_f32_16x16x32_bf16 v[52:55], v[160:163], v[168:171], v[52:55]
	v_mfma_f32_16x16x32_bf16 v[40:43], v[148:151], v[176:179], v[40:43]
	v_mfma_f32_16x16x32_bf16 v[36:39], v[160:163], v[176:179], v[36:39]
	v_mfma_f32_16x16x32_bf16 v[24:27], v[148:151], v[184:187], v[24:27]
	v_mfma_f32_16x16x32_bf16 v[20:23], v[160:163], v[184:187], v[20:23]
	v_mfma_f32_16x16x32_bf16 v[8:11], v[148:151], v[192:195], v[8:11]
	v_mfma_f32_16x16x32_bf16 v[4:7], v[160:163], v[192:195], v[4:7]
	s_barrier
	s_add_i32 s69, 0, 0x18000
	s_add_i32 s70, 0, 0x1c000
	v_add_u32_e32 v136, s69, v204
	v_add_u32_e32 v160, s70, v204
	ds_read_b128 v[116:119], v136
	ds_read_b128 v[128:131], v136 offset:1024
	ds_read_b128 v[132:135], v136 offset:2048
	ds_read_b128 v[136:139], v136 offset:3072
	ds_read_b128 v[140:143], v160
	ds_read_b128 v[148:151], v160 offset:1024
	ds_read_b128 v[152:155], v160 offset:2048
	ds_read_b128 v[160:163], v160 offset:3072
	s_add_u32 s50, s50, 0x80000
	s_addc_u32 s51, s51, 0
	s_mov_b32 m0, s57
	ds_read_b128 v[164:167], v244 offset:32768
	ds_read_b128 v[168:171], v244 offset:33792
	ds_read_b128 v[172:175], v244 offset:34816
	ds_read_b128 v[176:179], v244 offset:35840
	ds_read_b128 v[180:183], v244 offset:36864
	ds_read_b128 v[184:187], v244 offset:37888
	ds_read_b128 v[188:191], v244 offset:38912
	ds_read_b128 v[192:195], v244 offset:39936
	global_load_lds_dwordx4 v216, s[50:51]
	s_mov_b32 m0, s58
	s_nop 0
	global_load_lds_dwordx4 v214, s[50:51]
	s_waitcnt vmcnt(8)
	s_waitcnt lgkmcnt(0)
	s_barrier
	s_waitcnt lgkmcnt(0)
	v_mfma_f32_16x16x32_bf16 v[156:159], v[116:119], v[164:167], v[156:159]
	v_mfma_f32_16x16x32_bf16 v[144:147], v[132:135], v[164:167], v[144:147]
	v_mfma_f32_16x16x32_bf16 v[112:115], v[116:119], v[172:175], v[112:115]
	v_mfma_f32_16x16x32_bf16 v[108:111], v[132:135], v[172:175], v[108:111]
	v_mfma_f32_16x16x32_bf16 v[96:99], v[116:119], v[180:183], v[96:99]
	v_mfma_f32_16x16x32_bf16 v[92:95], v[132:135], v[180:183], v[92:95]
	v_mfma_f32_16x16x32_bf16 v[80:83], v[116:119], v[188:191], v[80:83]
	v_mfma_f32_16x16x32_bf16 v[76:79], v[132:135], v[188:191], v[76:79]
	v_mfma_f32_16x16x32_bf16 v[156:159], v[128:131], v[168:171], v[156:159]
	v_mfma_f32_16x16x32_bf16 v[144:147], v[136:139], v[168:171], v[144:147]
	v_mfma_f32_16x16x32_bf16 v[112:115], v[128:131], v[176:179], v[112:115]
	v_mfma_f32_16x16x32_bf16 v[108:111], v[136:139], v[176:179], v[108:111]
	v_mfma_f32_16x16x32_bf16 v[96:99], v[128:131], v[184:187], v[96:99]
	v_mfma_f32_16x16x32_bf16 v[92:95], v[136:139], v[184:187], v[92:95]
	v_mfma_f32_16x16x32_bf16 v[80:83], v[128:131], v[192:195], v[80:83]
	v_mfma_f32_16x16x32_bf16 v[76:79], v[136:139], v[192:195], v[76:79]
	v_mfma_f32_16x16x32_bf16 v[124:127], v[140:143], v[164:167], v[124:127]
	v_mfma_f32_16x16x32_bf16 v[120:123], v[152:155], v[164:167], v[120:123]
	v_mfma_f32_16x16x32_bf16 v[104:107], v[140:143], v[172:175], v[104:107]
	v_mfma_f32_16x16x32_bf16 v[100:103], v[152:155], v[172:175], v[100:103]
	v_mfma_f32_16x16x32_bf16 v[88:91], v[140:143], v[180:183], v[88:91]
	v_mfma_f32_16x16x32_bf16 v[84:87], v[152:155], v[180:183], v[84:87]
	v_mfma_f32_16x16x32_bf16 v[72:75], v[140:143], v[188:191], v[72:75]
	v_mfma_f32_16x16x32_bf16 v[68:71], v[152:155], v[188:191], v[68:71]
	v_mfma_f32_16x16x32_bf16 v[124:127], v[148:151], v[168:171], v[124:127]
	v_mfma_f32_16x16x32_bf16 v[120:123], v[160:163], v[168:171], v[120:123]
	v_mfma_f32_16x16x32_bf16 v[104:107], v[148:151], v[176:179], v[104:107]
	v_mfma_f32_16x16x32_bf16 v[100:103], v[160:163], v[176:179], v[100:103]
	v_mfma_f32_16x16x32_bf16 v[88:91], v[148:151], v[184:187], v[88:91]
	v_mfma_f32_16x16x32_bf16 v[84:87], v[160:163], v[184:187], v[84:87]
	v_mfma_f32_16x16x32_bf16 v[72:75], v[148:151], v[192:195], v[72:75]
	v_mfma_f32_16x16x32_bf16 v[68:71], v[160:163], v[192:195], v[68:71]
	s_barrier
	s_add_u32 s50, s48, 0x8000
	s_addc_u32 s51, s49, 0
	s_add_i32 s69, s69, s52
	s_mov_b32 m0, s69
	ds_read_b128 v[164:167], v244 offset:49152
	ds_read_b128 v[168:171], v244 offset:50176
	ds_read_b128 v[172:175], v244 offset:51200
	ds_read_b128 v[176:179], v244 offset:52224
	ds_read_b128 v[180:183], v244 offset:53248
	ds_read_b128 v[184:187], v244 offset:54272
	ds_read_b128 v[188:191], v244 offset:55296
	ds_read_b128 v[192:195], v244 offset:56320
	global_load_lds_dwordx4 v2, s[50:51]
	s_add_i32 m0, s69, 0x2000
	s_add_u32 s48, s48, 0xc000
	v_lshl_add_u64 v[226:227], s[50:51], 0, v[196:197]
	s_addc_u32 s49, s49, 0
	s_add_i32 s50, s70, s52
	global_load_lds_dwordx4 v[226:227], off
	s_mov_b32 m0, s50
	v_lshl_add_u64 v[222:223], v[222:223], 0, s[4:5]
	global_load_lds_dwordx4 v2, s[48:49]
	s_add_i32 m0, s50, 0x2000
	s_nop 0
	global_load_lds_dwordx4 v196, s[48:49]
	s_mov_b32 m0, s59
	s_nop 0
	global_load_lds_dwordx4 v[222:223], off
	v_lshl_add_u64 v[222:223], v[224:225], 0, s[4:5]
	s_mov_b32 m0, s60
	s_nop 0
	global_load_lds_dwordx4 v[222:223], off
	s_waitcnt vmcnt(8)
	s_waitcnt lgkmcnt(0)
	s_barrier
	s_waitcnt lgkmcnt(0)
	v_mfma_f32_16x16x32_bf16 v[64:67], v[116:119], v[164:167], v[64:67]
	v_mfma_f32_16x16x32_bf16 v[60:63], v[132:135], v[164:167], v[60:63]
	v_mfma_f32_16x16x32_bf16 v[48:51], v[116:119], v[172:175], v[48:51]
	v_mfma_f32_16x16x32_bf16 v[44:47], v[132:135], v[172:175], v[44:47]
	v_mfma_f32_16x16x32_bf16 v[32:35], v[116:119], v[180:183], v[32:35]
	v_mfma_f32_16x16x32_bf16 v[28:31], v[132:135], v[180:183], v[28:31]
	v_mfma_f32_16x16x32_bf16 v[16:19], v[116:119], v[188:191], v[16:19]
	v_mfma_f32_16x16x32_bf16 v[12:15], v[132:135], v[188:191], v[12:15]
	v_mfma_f32_16x16x32_bf16 v[64:67], v[128:131], v[168:171], v[64:67]
	v_mfma_f32_16x16x32_bf16 v[60:63], v[136:139], v[168:171], v[60:63]
	v_mfma_f32_16x16x32_bf16 v[48:51], v[128:131], v[176:179], v[48:51]
	v_mfma_f32_16x16x32_bf16 v[44:47], v[136:139], v[176:179], v[44:47]
	v_mfma_f32_16x16x32_bf16 v[32:35], v[128:131], v[184:187], v[32:35]
	v_mfma_f32_16x16x32_bf16 v[28:31], v[136:139], v[184:187], v[28:31]
	v_mfma_f32_16x16x32_bf16 v[16:19], v[128:131], v[192:195], v[16:19]
	v_mfma_f32_16x16x32_bf16 v[12:15], v[136:139], v[192:195], v[12:15]
	v_mfma_f32_16x16x32_bf16 v[56:59], v[140:143], v[164:167], v[56:59]
	v_mfma_f32_16x16x32_bf16 v[52:55], v[152:155], v[164:167], v[52:55]
	v_mfma_f32_16x16x32_bf16 v[40:43], v[140:143], v[172:175], v[40:43]
	v_mfma_f32_16x16x32_bf16 v[36:39], v[152:155], v[172:175], v[36:39]
	v_mfma_f32_16x16x32_bf16 v[24:27], v[140:143], v[180:183], v[24:27]
	v_mfma_f32_16x16x32_bf16 v[20:23], v[152:155], v[180:183], v[20:23]
	v_mfma_f32_16x16x32_bf16 v[8:11], v[140:143], v[188:191], v[8:11]
	v_mfma_f32_16x16x32_bf16 v[4:7], v[152:155], v[188:191], v[4:7]
	v_mfma_f32_16x16x32_bf16 v[56:59], v[148:151], v[168:171], v[56:59]
	v_mfma_f32_16x16x32_bf16 v[52:55], v[160:163], v[168:171], v[52:55]
	v_mfma_f32_16x16x32_bf16 v[40:43], v[148:151], v[176:179], v[40:43]
	v_mfma_f32_16x16x32_bf16 v[36:39], v[160:163], v[176:179], v[36:39]
	v_mfma_f32_16x16x32_bf16 v[24:27], v[148:151], v[184:187], v[24:27]
	v_mfma_f32_16x16x32_bf16 v[20:23], v[160:163], v[184:187], v[20:23]
	v_mfma_f32_16x16x32_bf16 v[8:11], v[148:151], v[192:195], v[8:11]
	v_mfma_f32_16x16x32_bf16 v[4:7], v[160:163], v[192:195], v[4:7]
	s_barrier
	s_add_i32 s68, s68, 2
	s_add_u32 s66, s66, 0x10000
	s_addc_u32 s67, s67, 0
	s_add_u32 s34, s34, 0x100
	s_addc_u32 s35, s35, 0
	s_cmp_gt_u32 s68, 29
	s_cbranch_scc0 .LBB0_733
	s_and_b64 vcc, exec, s[6:7]
	s_cbranch_vccz .LBB0_736
	s_barrier
